# nt (non-temporal) hint on once-read streaming loads: P0b w_ada GEMV, P1 x rows, P7 X1 rows; on the v042 stack
# baseline (speedup 1.0000x reference)
.LBB0_100:
	s_add_i32 s22, s16, s19
	v_mad_i64_i32 v[16:17], s[20:21], s22, v5, v[8:9]
	global_load_dwordx2 v[16:17], v[16:17], off nt
	s_add_i32 s20, s22, 8
	s_add_i32 s23, s22, 16
	s_add_i32 s24, s22, 24
	s_add_i32 s25, s22, 32
	s_add_i32 s26, s22, 40
	s_add_i32 s27, s22, 48
	s_add_i32 s22, s22, 56
	v_mad_i64_i32 v[18:19], s[20:21], s20, v5, v[8:9]
	v_mad_i64_i32 v[20:21], s[20:21], s23, v5, v[8:9]
	v_mad_i64_i32 v[22:23], s[20:21], s24, v5, v[8:9]
	v_mad_i64_i32 v[24:25], s[20:21], s25, v5, v[8:9]
	v_mad_i64_i32 v[26:27], s[20:21], s26, v5, v[8:9]
	v_mad_i64_i32 v[28:29], s[20:21], s27, v5, v[8:9]
	v_mad_i64_i32 v[30:31], s[20:21], s22, v5, v[8:9]
	global_load_dwordx2 v[32:33], v[18:19], off nt
	global_load_dwordx2 v[34:35], v[20:21], off nt
	global_load_dwordx2 v[42:43], v[22:23], off nt
	global_load_dwordx2 v[44:45], v[24:25], off nt
	global_load_dwordx2 v[46:47], v[26:27], off nt
	global_load_dwordx2 v[48:49], v[28:29], off nt
	global_load_dwordx2 v[50:51], v[30:31], off nt
	v_mov_b32_e32 v24, s17
	v_add_u32_e32 v38, 0x8000, v24
	v_add_u32_e32 v37, 0x4000, v24
	ds_read2_b32 v[18:19], v24 offset1:8
	ds_read2_b32 v[20:21], v24 offset0:16 offset1:24
	ds_read2_b32 v[22:23], v24 offset0:32 offset1:40
	ds_read2_b32 v[24:25], v24 offset0:48 offset1:56
	ds_read2_b32 v[26:27], v37 offset1:8
	ds_read2_b32 v[28:29], v38 offset1:8
	ds_read2_b32 v[30:31], v37 offset0:16 offset1:24
	ds_read2_b32 v[52:53], v38 offset0:16 offset1:24
	ds_read2_b32 v[54:55], v37 offset0:32 offset1:40
	ds_read2_b32 v[56:57], v38 offset0:32 offset1:40
	ds_read2_b32 v[58:59], v37 offset0:48 offset1:56
	ds_read2_b32 v[60:61], v38 offset0:48 offset1:56
	s_waitcnt lgkmcnt(11)
	v_mov_b32_e32 v38, v19
	s_waitcnt lgkmcnt(7)
	v_mov_b32_e32 v66, v27
	s_waitcnt lgkmcnt(6)
	v_mov_b32_e32 v68, v29
	v_mov_b32_e32 v40, v21
	s_waitcnt lgkmcnt(5)
	v_mov_b32_e32 v70, v31
	s_waitcnt lgkmcnt(4)
	v_mov_b32_e32 v72, v53
	v_mov_b32_e32 v62, v23
	s_waitcnt lgkmcnt(3)
	v_mov_b32_e32 v74, v55
	s_waitcnt lgkmcnt(2)
	v_mov_b32_e32 v76, v57
	s_add_i32 s19, s19, 64
	s_addk_i32 s17, 0x100
	v_mov_b32_e32 v64, v25
	s_waitcnt lgkmcnt(1)
	v_mov_b32_e32 v78, v59
	s_waitcnt lgkmcnt(0)
	v_mov_b32_e32 v80, v61
	s_cmpk_eq_i32 s19, 0x400
	s_waitcnt vmcnt(7)
	v_pk_fma_f32 v[10:11], v[16:17], v[18:19], v[10:11] op_sel_hi:[1,0,1]
	v_pk_fma_f32 v[12:13], v[16:17], v[26:27], v[12:13] op_sel_hi:[1,0,1]
	v_pk_fma_f32 v[14:15], v[16:17], v[28:29], v[14:15] op_sel_hi:[1,0,1]
	s_waitcnt vmcnt(6)
	v_pk_fma_f32 v[10:11], v[32:33], v[38:39], v[10:11] op_sel_hi:[1,0,1]
	v_pk_fma_f32 v[12:13], v[32:33], v[66:67], v[12:13] op_sel_hi:[1,0,1]
	v_pk_fma_f32 v[14:15], v[32:33], v[68:69], v[14:15] op_sel_hi:[1,0,1]
	s_waitcnt vmcnt(5)
	v_pk_fma_f32 v[10:11], v[34:35], v[20:21], v[10:11] op_sel_hi:[1,0,1]
	v_pk_fma_f32 v[12:13], v[34:35], v[30:31], v[12:13] op_sel_hi:[1,0,1]
	v_pk_fma_f32 v[14:15], v[34:35], v[52:53], v[14:15] op_sel_hi:[1,0,1]
	s_waitcnt vmcnt(4)
	v_pk_fma_f32 v[10:11], v[42:43], v[40:41], v[10:11] op_sel_hi:[1,0,1]
	v_pk_fma_f32 v[12:13], v[42:43], v[70:71], v[12:13] op_sel_hi:[1,0,1]
	v_pk_fma_f32 v[14:15], v[42:43], v[72:73], v[14:15] op_sel_hi:[1,0,1]
	s_waitcnt vmcnt(3)
	v_pk_fma_f32 v[10:11], v[44:45], v[22:23], v[10:11] op_sel_hi:[1,0,1]
	v_pk_fma_f32 v[12:13], v[44:45], v[54:55], v[12:13] op_sel_hi:[1,0,1]
	v_pk_fma_f32 v[14:15], v[44:45], v[56:57], v[14:15] op_sel_hi:[1,0,1]
	s_waitcnt vmcnt(2)
	v_pk_fma_f32 v[10:11], v[46:47], v[62:63], v[10:11] op_sel_hi:[1,0,1]
	v_pk_fma_f32 v[12:13], v[46:47], v[74:75], v[12:13] op_sel_hi:[1,0,1]
	v_pk_fma_f32 v[14:15], v[46:47], v[76:77], v[14:15] op_sel_hi:[1,0,1]
	s_waitcnt vmcnt(1)
	v_pk_fma_f32 v[10:11], v[48:49], v[24:25], v[10:11] op_sel_hi:[1,0,1]
	v_pk_fma_f32 v[12:13], v[48:49], v[58:59], v[12:13] op_sel_hi:[1,0,1]
	v_pk_fma_f32 v[14:15], v[48:49], v[60:61], v[14:15] op_sel_hi:[1,0,1]
	s_waitcnt vmcnt(0)
	v_pk_fma_f32 v[10:11], v[50:51], v[64:65], v[10:11] op_sel_hi:[1,0,1]
	v_pk_fma_f32 v[12:13], v[50:51], v[78:79], v[12:13] op_sel_hi:[1,0,1]
	v_pk_fma_f32 v[14:15], v[50:51], v[80:81], v[14:15] op_sel_hi:[1,0,1]
	s_cbranch_scc0 .LBB0_100
	ds_write2st64_b64 v3, v[10:11], v[12:13] offset0:96 offset1:97
	ds_write_b64 v3, v[14:15] offset:50176
	s_waitcnt lgkmcnt(0)
	s_barrier
	s_and_saveexec_b64 s[16:17], vcc
	s_cbranch_execz .LBB0_98
	ds_read2st64_b32 v[8:9], v1 offset0:192 offset1:198
	ds_read2st64_b32 v[10:11], v1 offset0:204 offset1:210
	ds_read2st64_b32 v[12:13], v1 offset0:216 offset1:222
	ds_read2st64_b32 v[14:15], v1 offset0:228 offset1:234
	s_waitcnt lgkmcnt(3)
	v_add_f32_e32 v8, 0, v8
	v_add_f32_e32 v8, v8, v9
	s_waitcnt lgkmcnt(2)
	v_add_f32_e32 v8, v8, v10
	v_add_f32_e32 v8, v8, v11
	s_waitcnt lgkmcnt(1)
	v_add_f32_e32 v8, v8, v12
	v_add_f32_e32 v8, v8, v13
	s_waitcnt lgkmcnt(0)
	v_add_f32_e32 v8, v8, v14
	v_add_f32_e32 v12, v8, v15
	v_mad_u64_u32 v[8:9], s[20:21], s11, 3, v[4:5]
	v_mov_b64_e32 v[10:11], s[6:7]
	s_ashr_i32 s11, s10, 31
	v_mad_i64_i32 v[8:9], s[20:21], v8, s5, v[10:11]
	v_lshl_add_u64 v[8:9], s[10:11], 2, v[8:9]
	v_lshl_add_u64 v[8:9], v[8:9], 0, v[6:7]
	global_store_dword v[8:9], v12, off
	s_branch .LBB0_98

.LBB0_216:
	v_mov_b32_e32 v70, v1
	s_lshl_b64 s[24:25], s[6:7], 12
	v_ashrrev_i32_e32 v71, 31, v70
	v_lshl_add_u64 v[2:3], v[70:71], 4, s[22:23]
	v_add_co_u32_e32 v4, vcc, s36, v2
	global_load_dwordx4 v[62:65], v[2:3], off nt
	global_load_dwordx4 v[58:61], v[2:3], off offset:1024 nt
	global_load_dwordx4 v[54:57], v[2:3], off offset:2048 nt
	global_load_dwordx4 v[50:53], v[2:3], off offset:3072 nt
	v_addc_co_u32_e32 v5, vcc, 0, v3, vcc
	global_load_dwordx4 v[46:49], v[4:5], off offset:-4096 nt
	v_add_co_u32_e32 v6, vcc, s35, v2
	s_lshl_b64 s[6:7], s[6:7], 13
	s_nop 0
	v_addc_co_u32_e32 v7, vcc, 0, v3, vcc
	global_load_dwordx4 v[42:45], v[6:7], off offset:1024 nt
	global_load_dwordx4 v[38:41], v[6:7], off offset:2048 nt
	global_load_dwordx4 v[34:37], v[6:7], off offset:3072 nt
	global_load_dwordx4 v[30:33], v[4:5], off nt
	global_load_dwordx4 v[26:29], v[4:5], off offset:1024 nt
	global_load_dwordx4 v[22:25], v[4:5], off offset:2048 nt
	global_load_dwordx4 v[18:21], v[4:5], off offset:3072 nt
	v_add_co_u32_e32 v74, vcc, s37, v2
	s_add_u32 s22, s3, s6
	s_nop 0
	v_addc_co_u32_e32 v75, vcc, 0, v3, vcc
	global_load_dwordx4 v[14:17], v[74:75], off nt
	global_load_dwordx4 v[10:13], v[74:75], off offset:1024 nt
	global_load_dwordx4 v[6:9], v[74:75], off offset:2048 nt
	global_load_dwordx4 v[2:5], v[74:75], off offset:3072 nt
	s_addc_u32 s23, s5, s7
	s_add_u32 s24, s26, s24
	s_addc_u32 s25, s27, s25
	s_waitcnt vmcnt(15)
	v_mul_f32_e32 v68, v63, v63
	v_mul_f32_e32 v73, v65, v65
	s_waitcnt vmcnt(14)
	v_mul_f32_e32 v74, v59, v59
	v_mul_f32_e32 v75, v61, v61
	s_waitcnt vmcnt(13)
	v_mul_f32_e32 v76, v55, v55
	v_mul_f32_e32 v77, v57, v57
	v_fmac_f32_e32 v68, v62, v62
	v_fmac_f32_e32 v73, v64, v64
	v_fmac_f32_e32 v74, v58, v58
	v_fmac_f32_e32 v75, v60, v60
	s_waitcnt vmcnt(12)
	v_mul_f32_e32 v78, v51, v51
	v_mul_f32_e32 v79, v53, v53
	v_fmac_f32_e32 v76, v54, v54
	v_fmac_f32_e32 v77, v56, v56
	v_add_f32_e32 v68, v68, v73
	v_add_f32_e32 v73, v74, v75
	v_fmac_f32_e32 v78, v50, v50
	v_fmac_f32_e32 v79, v52, v52
	s_waitcnt vmcnt(11)
	v_mul_f32_e32 v80, v47, v47
	v_mul_f32_e32 v81, v49, v49
	v_add_f32_e32 v74, v76, v77
	v_add_f32_e32 v68, v68, v73
	s_waitcnt vmcnt(10)
	v_mul_f32_e32 v82, v43, v43
	v_mul_f32_e32 v83, v45, v45
	v_add_f32_e32 v75, v78, v79
	v_fmac_f32_e32 v80, v46, v46
	v_fmac_f32_e32 v81, v48, v48
	v_add_f32_e32 v68, v68, v74
	s_waitcnt vmcnt(9)
	v_mul_f32_e32 v84, v39, v39
	v_mul_f32_e32 v85, v41, v41
	v_fmac_f32_e32 v82, v42, v42
	v_fmac_f32_e32 v83, v44, v44
	v_add_f32_e32 v73, v80, v81
	v_add_f32_e32 v68, v68, v75
	s_waitcnt vmcnt(8)
	v_mul_f32_e32 v86, v35, v35
	v_mul_f32_e32 v87, v37, v37
	v_fmac_f32_e32 v84, v38, v38
	v_fmac_f32_e32 v85, v40, v40
	v_add_f32_e32 v76, v82, v83
	v_add_f32_e32 v68, v68, v73
	s_waitcnt vmcnt(7)
	v_mul_f32_e32 v88, v31, v31
	v_mul_f32_e32 v89, v33, v33
	v_fmac_f32_e32 v86, v34, v34
	v_fmac_f32_e32 v87, v36, v36
	v_add_f32_e32 v77, v84, v85
	v_add_f32_e32 v68, v68, v76
	s_waitcnt vmcnt(6)
	v_mul_f32_e32 v90, v27, v27
	v_mul_f32_e32 v91, v29, v29
	v_fmac_f32_e32 v88, v30, v30
	v_fmac_f32_e32 v89, v32, v32
	v_add_f32_e32 v78, v86, v87
	v_add_f32_e32 v68, v68, v77
	s_waitcnt vmcnt(5)
	v_mul_f32_e32 v92, v23, v23
	v_mul_f32_e32 v93, v25, v25
	v_fmac_f32_e32 v90, v26, v26
	v_fmac_f32_e32 v91, v28, v28
	v_add_f32_e32 v79, v88, v89
	v_add_f32_e32 v68, v68, v78
	v_fmac_f32_e32 v92, v22, v22
	v_fmac_f32_e32 v93, v24, v24
	v_add_f32_e32 v80, v90, v91
	v_add_f32_e32 v68, v68, v79
	s_waitcnt vmcnt(4)
	v_mul_f32_e32 v73, v19, v19
	v_mul_f32_e32 v74, v21, v21
	v_add_f32_e32 v81, v92, v93
	v_add_f32_e32 v68, v68, v80
	v_fmac_f32_e32 v73, v18, v18
	v_fmac_f32_e32 v74, v20, v20
	v_add_f32_e32 v68, v68, v81
	v_add_f32_e32 v73, v73, v74
	v_add_f32_e32 v68, v68, v73
	s_waitcnt vmcnt(3)
	v_mul_f32_e32 v73, v15, v15
	v_mul_f32_e32 v74, v17, v17
	v_fmac_f32_e32 v73, v14, v14
	v_fmac_f32_e32 v74, v16, v16
	v_add_f32_e32 v73, v73, v74
	v_add_f32_e32 v68, v68, v73
	s_waitcnt vmcnt(2)
	v_mul_f32_e32 v73, v11, v11
	v_mul_f32_e32 v74, v13, v13
	v_fmac_f32_e32 v73, v10, v10
	v_fmac_f32_e32 v74, v12, v12
	v_add_f32_e32 v73, v73, v74
	v_add_f32_e32 v68, v68, v73
	s_waitcnt vmcnt(1)
	v_mul_f32_e32 v73, v7, v7
	v_mul_f32_e32 v74, v9, v9
	v_fmac_f32_e32 v73, v6, v6
	v_fmac_f32_e32 v74, v8, v8
	v_add_f32_e32 v73, v73, v74
	v_add_f32_e32 v68, v68, v73
	s_waitcnt vmcnt(0)
	v_mul_f32_e32 v73, v3, v3
	v_mul_f32_e32 v74, v5, v5
	v_fmac_f32_e32 v73, v2, v2
	v_fmac_f32_e32 v74, v4, v4
	v_add_f32_e32 v73, v73, v74
	v_add_f32_e32 v68, v68, v73
	ds_swizzle_b32 v73, v68 offset:swizzle(SWAP,1)
	s_waitcnt lgkmcnt(0)
	v_add_f32_e32 v68, v68, v73
	ds_swizzle_b32 v73, v68 offset:swizzle(SWAP,2)
	s_waitcnt lgkmcnt(0)
	v_add_f32_e32 v68, v68, v73
	ds_swizzle_b32 v73, v68 offset:swizzle(SWAP,4)
	s_waitcnt lgkmcnt(0)
	v_add_f32_e32 v68, v68, v73
	ds_swizzle_b32 v73, v68 offset:swizzle(SWAP,8)
	s_waitcnt lgkmcnt(0)
	v_add_f32_e32 v68, v68, v73
	ds_swizzle_b32 v73, v68 offset:swizzle(SWAP,16)
	s_waitcnt lgkmcnt(0)
	v_add_f32_e32 v68, v68, v73
	v_mov_b32_e32 v73, v68
	s_nop 1
	v_permlane32_swap_b32_e32 v68, v73
	v_add_f32_e32 v68, v68, v73
	v_fmamk_f32 v68, v68, 0x39800000, v67
	v_mul_f32_e32 v73, 0x4f800000, v68
	v_cmp_gt_f32_e32 vcc, s38, v68
	s_nop 1
	v_cndmask_b32_e32 v68, v68, v73, vcc
	v_sqrt_f32_e32 v73, v68
	s_nop 0
	v_add_u32_e32 v74, -1, v73
	v_fma_f32 v75, -v74, v73, v68
	v_cmp_ge_f32_e64 s[6:7], 0, v75
	v_add_u32_e32 v75, 1, v73
	s_nop 0
	v_cndmask_b32_e64 v74, v73, v74, s[6:7]
	v_fma_f32 v73, -v75, v73, v68
	v_cmp_lt_f32_e64 s[6:7], 0, v73
	s_nop 1
	v_cndmask_b32_e64 v73, v74, v75, s[6:7]
	v_mul_f32_e32 v74, 0x37800000, v73
	v_cndmask_b32_e32 v73, v73, v74, vcc
	v_cmp_class_f32_e32 vcc, v68, v69
	s_nop 1
	v_cndmask_b32_e32 v68, v73, v68, vcc
	v_div_scale_f32 v73, s[6:7], v68, v68, 1.0
	v_rcp_f32_e32 v74, v73
	s_lshl_b32 s6, s42, 2
	s_add_i32 s6, s6, 0
	s_add_u32 s12, s12, s14
	v_fma_f32 v75, -v73, v74, 1.0
	v_fmac_f32_e32 v74, v75, v74
	v_div_scale_f32 v75, vcc, 1.0, v68, 1.0
	v_mul_f32_e32 v76, v75, v74
	v_fma_f32 v77, -v73, v76, v75
	v_fmac_f32_e32 v76, v77, v74
	v_fma_f32 v73, -v73, v76, v75
	v_div_fmas_f32 v73, v73, v74, v76
	v_div_fixup_f32 v68, v73, v68, 1.0
	v_lshlrev_b32_e32 v73, 4, v70
	v_add_u32_e32 v74, 0, v73
	v_add_u32_e32 v74, 0x18000, v74
	v_add_u32_e32 v73, s6, v73
	ds_read_b128 v[76:79], v74
	ds_read_b128 v[80:83], v73
	ds_read_b128 v[84:87], v73 offset:49152
	v_pk_mul_f32 v[62:63], v[62:63], v[68:69] op_sel_hi:[1,0]
	v_pk_mul_f32 v[64:65], v[64:65], v[68:69] op_sel_hi:[1,0]
	ds_read_b128 v[88:91], v74 offset:1024
	s_waitcnt lgkmcnt(3)
	v_pk_mul_f32 v[62:63], v[76:77], v[62:63]
	s_waitcnt lgkmcnt(1)
	v_pk_add_f32 v[94:95], v[84:85], 1.0 op_sel_hi:[1,0]
	v_pk_mul_f32 v[64:65], v[78:79], v[64:65]
	ds_read_b128 v[76:79], v73 offset:50176
	v_pk_fma_f32 v[80:81], v[94:95], v[62:63], v[80:81]
	v_pk_add_f32 v[92:93], v[86:87], 1.0 op_sel_hi:[1,0]
	ds_read_b128 v[84:87], v73 offset:1024
	v_med3_f32 v62, v80, s39, v72
	v_med3_f32 v63, v81, s39, v72
	v_mov_b32_e32 v75, 0
	v_cvt_pk_fp8_f32 v75, v62, v63
	v_pk_fma_f32 v[82:83], v[92:93], v[64:65], v[82:83]
	v_pk_mul_f32 v[58:59], v[58:59], v[68:69] op_sel_hi:[1,0]
	v_med3_f32 v62, v82, s39, v72
	v_med3_f32 v63, v83, s39, v72
	s_waitcnt lgkmcnt(2)
	v_pk_mul_f32 v[58:59], v[88:89], v[58:59]
	s_waitcnt lgkmcnt(1)
	v_pk_add_f32 v[76:77], v[76:77], 1.0 op_sel_hi:[1,0]
	v_cvt_pk_fp8_f32 v75, v62, v63 op_sel:[0,0,1]
	v_lshl_add_u64 v[64:65], v[70:71], 3, s[22:23]
	v_lshl_add_u64 v[62:63], v[70:71], 2, s[24:25]
	v_bfe_u32 v70, v80, 16, 1
	s_waitcnt lgkmcnt(0)
	v_pk_fma_f32 v[58:59], v[76:77], v[58:59], v[84:85]
	v_add3_u32 v70, v80, v70, s40
	v_med3_f32 v76, v58, s39, v72
	v_med3_f32 v77, v59, s39, v72
	v_mov_b32_e32 v80, 0
	v_pk_mul_f32 v[60:61], v[60:61], v[68:69] op_sel_hi:[1,0]
	v_cvt_pk_fp8_f32 v80, v76, v77
	v_bfe_u32 v71, v81, 16, 1
	v_pk_mul_f32 v[60:61], v[90:91], v[60:61]
	v_pk_add_f32 v[78:79], v[78:79], 1.0 op_sel_hi:[1,0]
	v_lshrrev_b32_e32 v70, 16, v70
	v_add3_u32 v71, v81, v71, s40
	v_pk_fma_f32 v[60:61], v[78:79], v[60:61], v[86:87]
	v_and_or_b32 v70, v71, s41, v70
	v_bfe_u32 v71, v82, 16, 1
	v_med3_f32 v76, v60, s39, v72
	v_med3_f32 v77, v61, s39, v72
	global_store_dword v[62:63], v75, off
	v_add3_u32 v71, v82, v71, s40
	v_bfe_u32 v75, v83, 16, 1
	v_cvt_pk_fp8_f32 v80, v76, v77 op_sel:[0,0,1]
	v_lshrrev_b32_e32 v71, 16, v71
	v_add3_u32 v75, v83, v75, s40
	v_and_or_b32 v71, v75, s41, v71
	global_store_dwordx2 v[64:65], v[70:71], off
	global_store_dword v[62:63], v80, off offset:256
	v_bfe_u32 v70, v58, 16, 1
	v_add3_u32 v58, v58, v70, s40
	v_bfe_u32 v70, v59, 16, 1
	v_lshrrev_b32_e32 v58, 16, v58
	v_add3_u32 v59, v59, v70, s40
	v_and_or_b32 v58, v59, s41, v58
	v_bfe_u32 v59, v60, 16, 1
	v_add3_u32 v59, v60, v59, s40
	v_bfe_u32 v60, v61, 16, 1
	v_lshrrev_b32_e32 v59, 16, v59
	v_add3_u32 v60, v61, v60, s40
	v_and_or_b32 v59, v60, s41, v59
	global_store_dwordx2 v[64:65], v[58:59], off offset:512
	ds_read_b128 v[58:61], v74 offset:2048
	ds_read_b128 v[76:79], v73 offset:2048
	ds_read_b128 v[80:83], v73 offset:51200
	v_pk_mul_f32 v[70:71], v[56:57], v[68:69] op_sel_hi:[1,0]
	v_pk_mul_f32 v[84:85], v[54:55], v[68:69] op_sel_hi:[1,0]
	ds_read_b128 v[54:57], v74 offset:3072
	s_waitcnt lgkmcnt(3)
	v_pk_mul_f32 v[84:85], v[84:85], v[58:59]
	v_pk_mul_f32 v[70:71], v[70:71], v[60:61]
	ds_read_b128 v[58:61], v73 offset:52224
	s_waitcnt lgkmcnt(2)
	v_pk_add_f32 v[88:89], v[80:81], 1.0 op_sel_hi:[1,0]
	v_pk_add_f32 v[86:87], v[82:83], 1.0 op_sel_hi:[1,0]
	ds_read_b128 v[80:83], v73 offset:3072
	v_pk_fma_f32 v[76:77], v[84:85], v[88:89], v[76:77]
	v_mov_b32_e32 v85, 0
	v_med3_f32 v75, v76, s39, v72
	v_med3_f32 v84, v77, s39, v72
	v_cvt_pk_fp8_f32 v85, v75, v84
	v_pk_mul_f32 v[52:53], v[52:53], v[68:69] op_sel_hi:[1,0]
	v_pk_mul_f32 v[50:51], v[50:51], v[68:69] op_sel_hi:[1,0]
	v_pk_fma_f32 v[70:71], v[70:71], v[86:87], v[78:79]
	s_waitcnt lgkmcnt(2)
	v_pk_mul_f32 v[50:51], v[50:51], v[54:55]
	v_pk_mul_f32 v[52:53], v[52:53], v[56:57]
	s_waitcnt lgkmcnt(1)
	v_pk_add_f32 v[56:57], v[58:59], 1.0 op_sel_hi:[1,0]
	v_med3_f32 v75, v70, s39, v72
	v_med3_f32 v78, v71, s39, v72
	s_waitcnt lgkmcnt(0)
	v_pk_fma_f32 v[50:51], v[50:51], v[56:57], v[80:81]
	v_cvt_pk_fp8_f32 v85, v75, v78 op_sel:[0,0,1]
	v_bfe_u32 v75, v76, 16, 1
	v_med3_f32 v56, v50, s39, v72
	v_med3_f32 v57, v51, s39, v72
	v_mov_b32_e32 v58, 0
	v_add3_u32 v75, v76, v75, s40
	v_bfe_u32 v76, v77, 16, 1
	v_cvt_pk_fp8_f32 v58, v56, v57
	v_lshrrev_b32_e32 v75, 16, v75
	v_add3_u32 v76, v77, v76, s40
	v_pk_add_f32 v[54:55], v[60:61], 1.0 op_sel_hi:[1,0]
	v_and_or_b32 v76, v76, s41, v75
	v_bfe_u32 v75, v70, 16, 1
	v_pk_fma_f32 v[52:53], v[52:53], v[54:55], v[82:83]
	v_add3_u32 v70, v70, v75, s40
	v_bfe_u32 v75, v71, 16, 1
	v_med3_f32 v54, v52, s39, v72
	v_med3_f32 v55, v53, s39, v72
	v_lshrrev_b32_e32 v70, 16, v70
	v_cvt_pk_fp8_f32 v58, v54, v55 op_sel:[0,0,1]
	v_add3_u32 v54, v71, v75, s40
	v_and_or_b32 v77, v54, s41, v70
	v_bfe_u32 v54, v50, 16, 1
	v_add3_u32 v50, v50, v54, s40
	v_bfe_u32 v54, v51, 16, 1
	v_lshrrev_b32_e32 v50, 16, v50
	v_add3_u32 v51, v51, v54, s40
	v_and_or_b32 v50, v51, s41, v50
	v_bfe_u32 v51, v52, 16, 1
	v_add3_u32 v51, v52, v51, s40
	v_bfe_u32 v52, v53, 16, 1
	v_lshrrev_b32_e32 v51, 16, v51
	v_add3_u32 v52, v53, v52, s40
	v_and_or_b32 v51, v52, s41, v51
	global_store_dword v[62:63], v85, off offset:512
	global_store_dwordx2 v[64:65], v[76:77], off offset:1024
	global_store_dword v[62:63], v58, off offset:768
	global_store_dwordx2 v[64:65], v[50:51], off offset:1536
	ds_read_b128 v[50:53], v74 offset:4096
	ds_read_b128 v[54:57], v73 offset:4096
	ds_read_b128 v[58:61], v73 offset:53248
	v_pk_mul_f32 v[70:71], v[48:49], v[68:69] op_sel_hi:[1,0]
	v_pk_mul_f32 v[76:77], v[46:47], v[68:69] op_sel_hi:[1,0]
	ds_read_b128 v[46:49], v74 offset:5120
	s_waitcnt lgkmcnt(3)
	v_pk_mul_f32 v[76:77], v[76:77], v[50:51]
	v_pk_mul_f32 v[70:71], v[70:71], v[52:53]
	ds_read_b128 v[50:53], v73 offset:54272
	s_waitcnt lgkmcnt(2)
	v_pk_add_f32 v[80:81], v[58:59], 1.0 op_sel_hi:[1,0]
	v_pk_add_f32 v[78:79], v[60:61], 1.0 op_sel_hi:[1,0]
	ds_read_b128 v[58:61], v73 offset:5120
	v_pk_fma_f32 v[54:55], v[76:77], v[80:81], v[54:55]
	v_mov_b32_e32 v77, 0
	v_med3_f32 v75, v54, s39, v72
	v_med3_f32 v76, v55, s39, v72
	v_cvt_pk_fp8_f32 v77, v75, v76
	v_pk_mul_f32 v[44:45], v[44:45], v[68:69] op_sel_hi:[1,0]
	v_pk_mul_f32 v[42:43], v[42:43], v[68:69] op_sel_hi:[1,0]
	v_pk_fma_f32 v[56:57], v[70:71], v[78:79], v[56:57]
	s_waitcnt lgkmcnt(2)
	v_pk_mul_f32 v[42:43], v[42:43], v[46:47]
	v_pk_mul_f32 v[44:45], v[44:45], v[48:49]
	s_waitcnt lgkmcnt(1)
	v_pk_add_f32 v[48:49], v[50:51], 1.0 op_sel_hi:[1,0]
	v_med3_f32 v70, v56, s39, v72
	v_med3_f32 v71, v57, s39, v72
	s_waitcnt lgkmcnt(0)
	v_pk_fma_f32 v[42:43], v[42:43], v[48:49], v[58:59]
	v_cvt_pk_fp8_f32 v77, v70, v71 op_sel:[0,0,1]
	v_bfe_u32 v70, v54, 16, 1
	v_med3_f32 v48, v42, s39, v72
	v_med3_f32 v49, v43, s39, v72
	v_mov_b32_e32 v50, 0
	v_add3_u32 v54, v54, v70, s40
	v_bfe_u32 v70, v55, 16, 1
	v_cvt_pk_fp8_f32 v50, v48, v49
	v_lshrrev_b32_e32 v54, 16, v54
	v_add3_u32 v55, v55, v70, s40
	v_pk_add_f32 v[46:47], v[52:53], 1.0 op_sel_hi:[1,0]
	v_and_or_b32 v54, v55, s41, v54
	v_bfe_u32 v55, v56, 16, 1
	v_pk_fma_f32 v[44:45], v[44:45], v[46:47], v[60:61]
	v_add3_u32 v55, v56, v55, s40
	v_bfe_u32 v56, v57, 16, 1
	v_med3_f32 v46, v44, s39, v72
	v_med3_f32 v47, v45, s39, v72
	v_lshrrev_b32_e32 v55, 16, v55
	v_cvt_pk_fp8_f32 v50, v46, v47 op_sel:[0,0,1]
	v_add3_u32 v46, v57, v56, s40
	v_and_or_b32 v55, v46, s41, v55
	v_bfe_u32 v46, v42, 16, 1
	v_add3_u32 v42, v42, v46, s40
	v_bfe_u32 v46, v43, 16, 1
	v_lshrrev_b32_e32 v42, 16, v42
	v_add3_u32 v43, v43, v46, s40
	v_and_or_b32 v42, v43, s41, v42
	v_bfe_u32 v43, v44, 16, 1
	v_add3_u32 v43, v44, v43, s40
	v_bfe_u32 v44, v45, 16, 1
	v_lshrrev_b32_e32 v43, 16, v43
	v_add3_u32 v44, v45, v44, s40
	v_and_or_b32 v43, v44, s41, v43
	global_store_dword v[62:63], v77, off offset:1024
	global_store_dwordx2 v[64:65], v[54:55], off offset:2048
	global_store_dword v[62:63], v50, off offset:1280
	global_store_dwordx2 v[64:65], v[42:43], off offset:2560
	ds_read_b128 v[42:45], v74 offset:6144
	ds_read_b128 v[46:49], v73 offset:6144
	ds_read_b128 v[50:53], v73 offset:55296
	v_pk_mul_f32 v[54:55], v[40:41], v[68:69] op_sel_hi:[1,0]
	v_pk_mul_f32 v[56:57], v[38:39], v[68:69] op_sel_hi:[1,0]
	ds_read_b128 v[38:41], v74 offset:7168
	s_waitcnt lgkmcnt(3)
	v_pk_mul_f32 v[56:57], v[56:57], v[42:43]
	v_pk_mul_f32 v[54:55], v[54:55], v[44:45]
	ds_read_b128 v[42:45], v73 offset:56320
	s_waitcnt lgkmcnt(2)
	v_pk_add_f32 v[60:61], v[50:51], 1.0 op_sel_hi:[1,0]
	v_pk_add_f32 v[58:59], v[52:53], 1.0 op_sel_hi:[1,0]
	ds_read_b128 v[50:53], v73 offset:7168
	v_pk_fma_f32 v[46:47], v[56:57], v[60:61], v[46:47]
	v_mov_b32_e32 v60, 0
	v_med3_f32 v56, v46, s39, v72
	v_med3_f32 v57, v47, s39, v72
	v_cvt_pk_fp8_f32 v60, v56, v57
	v_pk_mul_f32 v[36:37], v[36:37], v[68:69] op_sel_hi:[1,0]
	v_pk_mul_f32 v[34:35], v[34:35], v[68:69] op_sel_hi:[1,0]
	v_pk_fma_f32 v[48:49], v[54:55], v[58:59], v[48:49]
	s_waitcnt lgkmcnt(2)
	v_pk_mul_f32 v[34:35], v[34:35], v[38:39]
	v_pk_mul_f32 v[36:37], v[36:37], v[40:41]
	s_waitcnt lgkmcnt(1)
	v_pk_add_f32 v[40:41], v[42:43], 1.0 op_sel_hi:[1,0]
	v_med3_f32 v54, v48, s39, v72
	v_med3_f32 v55, v49, s39, v72
	s_waitcnt lgkmcnt(0)
	v_pk_fma_f32 v[34:35], v[34:35], v[40:41], v[50:51]
	v_cvt_pk_fp8_f32 v60, v54, v55 op_sel:[0,0,1]
	v_bfe_u32 v54, v46, 16, 1
	v_med3_f32 v40, v34, s39, v72
	v_med3_f32 v41, v35, s39, v72
	v_mov_b32_e32 v42, 0
	v_add3_u32 v46, v46, v54, s40
	v_bfe_u32 v54, v47, 16, 1
	v_cvt_pk_fp8_f32 v42, v40, v41
	v_lshrrev_b32_e32 v46, 16, v46
	v_add3_u32 v47, v47, v54, s40
	v_pk_add_f32 v[38:39], v[44:45], 1.0 op_sel_hi:[1,0]
	v_and_or_b32 v46, v47, s41, v46
	v_bfe_u32 v47, v48, 16, 1
	v_pk_fma_f32 v[36:37], v[36:37], v[38:39], v[52:53]
	v_add3_u32 v47, v48, v47, s40
	v_bfe_u32 v48, v49, 16, 1
	v_med3_f32 v38, v36, s39, v72
	v_med3_f32 v39, v37, s39, v72
	v_lshrrev_b32_e32 v47, 16, v47
	v_cvt_pk_fp8_f32 v42, v38, v39 op_sel:[0,0,1]
	v_add3_u32 v38, v49, v48, s40
	v_and_or_b32 v47, v38, s41, v47
	v_bfe_u32 v38, v34, 16, 1
	v_add3_u32 v34, v34, v38, s40
	v_bfe_u32 v38, v35, 16, 1
	v_lshrrev_b32_e32 v34, 16, v34
	v_add3_u32 v35, v35, v38, s40
	v_and_or_b32 v34, v35, s41, v34
	v_bfe_u32 v35, v36, 16, 1
	v_add3_u32 v35, v36, v35, s40
	v_bfe_u32 v36, v37, 16, 1
	v_lshrrev_b32_e32 v35, 16, v35
	v_add3_u32 v36, v37, v36, s40
	v_and_or_b32 v35, v36, s41, v35
	global_store_dword v[62:63], v60, off offset:1536
	global_store_dwordx2 v[64:65], v[46:47], off offset:3072
	global_store_dword v[62:63], v42, off offset:1792
	global_store_dwordx2 v[64:65], v[34:35], off offset:3584
	ds_read_b128 v[34:37], v74 offset:8192
	ds_read_b128 v[38:41], v73 offset:8192
	ds_read_b128 v[42:45], v73 offset:57344
	v_pk_mul_f32 v[46:47], v[32:33], v[68:69] op_sel_hi:[1,0]
	v_pk_mul_f32 v[48:49], v[30:31], v[68:69] op_sel_hi:[1,0]
	ds_read_b128 v[30:33], v74 offset:9216
	s_waitcnt lgkmcnt(3)
	v_pk_mul_f32 v[48:49], v[48:49], v[34:35]
	v_pk_mul_f32 v[46:47], v[46:47], v[36:37]
	ds_read_b128 v[34:37], v73 offset:58368
	s_waitcnt lgkmcnt(2)
	v_pk_add_f32 v[50:51], v[44:45], 1.0 op_sel_hi:[1,0]
	v_pk_add_f32 v[52:53], v[42:43], 1.0 op_sel_hi:[1,0]
	ds_read_b128 v[42:45], v73 offset:9216
	v_pk_fma_f32 v[38:39], v[48:49], v[52:53], v[38:39]
	v_mov_b32_e32 v52, 0
	v_med3_f32 v48, v38, s39, v72
	v_med3_f32 v49, v39, s39, v72
	v_cvt_pk_fp8_f32 v52, v48, v49
	v_pk_mul_f32 v[28:29], v[28:29], v[68:69] op_sel_hi:[1,0]
	v_pk_mul_f32 v[26:27], v[26:27], v[68:69] op_sel_hi:[1,0]
	s_waitcnt lgkmcnt(2)
	v_pk_mul_f32 v[28:29], v[28:29], v[32:33]
	v_pk_mul_f32 v[26:27], v[26:27], v[30:31]
	s_waitcnt lgkmcnt(1)
	v_pk_add_f32 v[32:33], v[34:35], 1.0 op_sel_hi:[1,0]
	v_pk_fma_f32 v[40:41], v[46:47], v[50:51], v[40:41]
	s_waitcnt lgkmcnt(0)
	v_pk_fma_f32 v[32:33], v[26:27], v[32:33], v[42:43]
	v_med3_f32 v46, v40, s39, v72
	v_med3_f32 v47, v41, s39, v72
	v_pk_add_f32 v[30:31], v[36:37], 1.0 op_sel_hi:[1,0]
	v_med3_f32 v26, v32, s39, v72
	v_med3_f32 v27, v33, s39, v72
	v_mov_b32_e32 v34, 0
	v_cvt_pk_fp8_f32 v52, v46, v47 op_sel:[0,0,1]
	v_bfe_u32 v46, v38, 16, 1
	v_cvt_pk_fp8_f32 v34, v26, v27
	v_pk_fma_f32 v[28:29], v[28:29], v[30:31], v[44:45]
	v_bfe_u32 v30, v32, 16, 1
	v_add3_u32 v38, v38, v46, s40
	v_bfe_u32 v46, v39, 16, 1
	v_add3_u32 v30, v32, v30, s40
	v_bfe_u32 v31, v33, 16, 1
	v_lshrrev_b32_e32 v38, 16, v38
	v_add3_u32 v39, v39, v46, s40
	v_lshrrev_b32_e32 v30, 16, v30
	v_add3_u32 v31, v33, v31, s40
	v_and_or_b32 v38, v39, s41, v38
	v_bfe_u32 v39, v40, 16, 1
	v_med3_f32 v26, v28, s39, v72
	v_med3_f32 v27, v29, s39, v72
	v_and_or_b32 v30, v31, s41, v30
	v_bfe_u32 v31, v28, 16, 1
	v_add3_u32 v39, v40, v39, s40
	v_bfe_u32 v40, v41, 16, 1
	v_cvt_pk_fp8_f32 v34, v26, v27 op_sel:[0,0,1]
	v_add3_u32 v28, v28, v31, s40
	v_bfe_u32 v31, v29, 16, 1
	v_lshrrev_b32_e32 v39, 16, v39
	v_add3_u32 v40, v41, v40, s40
	v_add_co_u32_e32 v26, vcc, s35, v64
	v_lshrrev_b32_e32 v28, 16, v28
	v_add3_u32 v29, v29, v31, s40
	v_and_or_b32 v39, v40, s41, v39
	v_addc_co_u32_e32 v27, vcc, 0, v65, vcc
	v_and_or_b32 v31, v29, s41, v28
	global_store_dword v[62:63], v52, off offset:2048
	global_store_dwordx2 v[26:27], v[38:39], off
	global_store_dword v[62:63], v34, off offset:2304
	global_store_dwordx2 v[26:27], v[30:31], off offset:512
	ds_read_b128 v[28:31], v74 offset:10240
	ds_read_b128 v[32:35], v73 offset:10240
	ds_read_b128 v[36:39], v73 offset:59392
	v_pk_mul_f32 v[40:41], v[24:25], v[68:69] op_sel_hi:[1,0]
	v_pk_mul_f32 v[42:43], v[22:23], v[68:69] op_sel_hi:[1,0]
	ds_read_b128 v[22:25], v74 offset:11264
	s_waitcnt lgkmcnt(3)
	v_pk_mul_f32 v[42:43], v[42:43], v[28:29]
	v_pk_mul_f32 v[40:41], v[40:41], v[30:31]
	ds_read_b128 v[28:31], v73 offset:60416
	s_waitcnt lgkmcnt(2)
	v_pk_add_f32 v[46:47], v[36:37], 1.0 op_sel_hi:[1,0]
	v_pk_add_f32 v[44:45], v[38:39], 1.0 op_sel_hi:[1,0]
	ds_read_b128 v[36:39], v73 offset:11264
	v_pk_fma_f32 v[32:33], v[42:43], v[46:47], v[32:33]
	v_mov_b32_e32 v46, 0
	v_med3_f32 v42, v32, s39, v72
	v_med3_f32 v43, v33, s39, v72
	v_cvt_pk_fp8_f32 v46, v42, v43
	v_pk_mul_f32 v[20:21], v[20:21], v[68:69] op_sel_hi:[1,0]
	v_pk_mul_f32 v[18:19], v[18:19], v[68:69] op_sel_hi:[1,0]
	v_pk_fma_f32 v[34:35], v[40:41], v[44:45], v[34:35]
	s_waitcnt lgkmcnt(2)
	v_pk_mul_f32 v[18:19], v[18:19], v[22:23]
	v_pk_mul_f32 v[20:21], v[20:21], v[24:25]
	s_waitcnt lgkmcnt(1)
	v_pk_add_f32 v[24:25], v[28:29], 1.0 op_sel_hi:[1,0]
	v_med3_f32 v40, v34, s39, v72
	v_med3_f32 v41, v35, s39, v72
	s_waitcnt lgkmcnt(0)
	v_pk_fma_f32 v[18:19], v[18:19], v[24:25], v[36:37]
	v_cvt_pk_fp8_f32 v46, v40, v41 op_sel:[0,0,1]
	v_bfe_u32 v40, v32, 16, 1
	v_med3_f32 v24, v18, s39, v72
	v_med3_f32 v25, v19, s39, v72
	v_mov_b32_e32 v28, 0
	v_add3_u32 v32, v32, v40, s40
	v_bfe_u32 v40, v33, 16, 1
	v_cvt_pk_fp8_f32 v28, v24, v25
	v_lshrrev_b32_e32 v32, 16, v32
	v_add3_u32 v33, v33, v40, s40
	v_pk_add_f32 v[22:23], v[30:31], 1.0 op_sel_hi:[1,0]
	v_and_or_b32 v32, v33, s41, v32
	v_bfe_u32 v33, v34, 16, 1
	v_pk_fma_f32 v[20:21], v[20:21], v[22:23], v[38:39]
	v_add3_u32 v33, v34, v33, s40
	v_bfe_u32 v34, v35, 16, 1
	v_med3_f32 v22, v20, s39, v72
	v_med3_f32 v23, v21, s39, v72
	v_lshrrev_b32_e32 v33, 16, v33
	v_cvt_pk_fp8_f32 v28, v22, v23 op_sel:[0,0,1]
	v_add3_u32 v22, v35, v34, s40
	v_and_or_b32 v33, v22, s41, v33
	v_bfe_u32 v22, v18, 16, 1
	v_add3_u32 v18, v18, v22, s40
	v_bfe_u32 v22, v19, 16, 1
	v_lshrrev_b32_e32 v18, 16, v18
	v_add3_u32 v19, v19, v22, s40
	v_and_or_b32 v18, v19, s41, v18
	v_bfe_u32 v19, v20, 16, 1
	v_add3_u32 v19, v20, v19, s40
	v_bfe_u32 v20, v21, 16, 1
	v_lshrrev_b32_e32 v19, 16, v19
	v_add3_u32 v20, v21, v20, s40
	v_and_or_b32 v19, v20, s41, v19
	global_store_dword v[62:63], v46, off offset:2560
	global_store_dwordx2 v[26:27], v[32:33], off offset:1024
	global_store_dword v[62:63], v28, off offset:2816
	global_store_dwordx2 v[26:27], v[18:19], off offset:1536
	ds_read_b128 v[18:21], v74 offset:12288
	ds_read_b128 v[22:25], v73 offset:12288
	ds_read_b128 v[28:31], v73 offset:61440
	v_pk_mul_f32 v[32:33], v[16:17], v[68:69] op_sel_hi:[1,0]
	v_pk_mul_f32 v[34:35], v[14:15], v[68:69] op_sel_hi:[1,0]
	ds_read_b128 v[14:17], v74 offset:13312
	s_waitcnt lgkmcnt(3)
	v_pk_mul_f32 v[34:35], v[34:35], v[18:19]
	v_pk_mul_f32 v[32:33], v[32:33], v[20:21]
	ds_read_b128 v[18:21], v73 offset:62464
	s_waitcnt lgkmcnt(2)
	v_pk_add_f32 v[38:39], v[28:29], 1.0 op_sel_hi:[1,0]
	v_pk_add_f32 v[36:37], v[30:31], 1.0 op_sel_hi:[1,0]
	ds_read_b128 v[28:31], v73 offset:13312
	v_pk_fma_f32 v[22:23], v[34:35], v[38:39], v[22:23]
	v_mov_b32_e32 v38, 0
	v_med3_f32 v34, v22, s39, v72
	v_med3_f32 v35, v23, s39, v72
	v_cvt_pk_fp8_f32 v38, v34, v35
	v_pk_mul_f32 v[12:13], v[12:13], v[68:69] op_sel_hi:[1,0]
	v_pk_mul_f32 v[10:11], v[10:11], v[68:69] op_sel_hi:[1,0]
	v_pk_fma_f32 v[24:25], v[32:33], v[36:37], v[24:25]
	s_waitcnt lgkmcnt(2)
	v_pk_mul_f32 v[10:11], v[10:11], v[14:15]
	v_pk_mul_f32 v[12:13], v[12:13], v[16:17]
	s_waitcnt lgkmcnt(1)
	v_pk_add_f32 v[16:17], v[18:19], 1.0 op_sel_hi:[1,0]
	v_med3_f32 v32, v24, s39, v72
	v_med3_f32 v33, v25, s39, v72
	s_waitcnt lgkmcnt(0)
	v_pk_fma_f32 v[10:11], v[10:11], v[16:17], v[28:29]
	v_cvt_pk_fp8_f32 v38, v32, v33 op_sel:[0,0,1]
	v_bfe_u32 v32, v22, 16, 1
	v_med3_f32 v16, v10, s39, v72
	v_med3_f32 v17, v11, s39, v72
	v_mov_b32_e32 v18, 0
	v_add3_u32 v22, v22, v32, s40
	v_bfe_u32 v32, v23, 16, 1
	v_cvt_pk_fp8_f32 v18, v16, v17
	v_lshrrev_b32_e32 v22, 16, v22
	v_add3_u32 v23, v23, v32, s40
	v_pk_add_f32 v[14:15], v[20:21], 1.0 op_sel_hi:[1,0]
	v_and_or_b32 v22, v23, s41, v22
	v_bfe_u32 v23, v24, 16, 1
	v_pk_fma_f32 v[12:13], v[12:13], v[14:15], v[30:31]
	v_add3_u32 v23, v24, v23, s40
	v_bfe_u32 v24, v25, 16, 1
	v_med3_f32 v14, v12, s39, v72
	v_med3_f32 v15, v13, s39, v72
	v_lshrrev_b32_e32 v23, 16, v23
	v_cvt_pk_fp8_f32 v18, v14, v15 op_sel:[0,0,1]
	v_add3_u32 v14, v25, v24, s40
	v_and_or_b32 v23, v14, s41, v23
	v_bfe_u32 v14, v10, 16, 1
	v_add3_u32 v10, v10, v14, s40
	v_bfe_u32 v14, v11, 16, 1
	v_lshrrev_b32_e32 v10, 16, v10
	v_add3_u32 v11, v11, v14, s40
	v_and_or_b32 v10, v11, s41, v10
	v_bfe_u32 v11, v12, 16, 1
	v_add3_u32 v11, v12, v11, s40
	v_bfe_u32 v12, v13, 16, 1
	v_lshrrev_b32_e32 v11, 16, v11
	v_add3_u32 v12, v13, v12, s40
	v_and_or_b32 v11, v12, s41, v11
	global_store_dword v[62:63], v38, off offset:3072
	global_store_dwordx2 v[26:27], v[22:23], off offset:2048
	global_store_dword v[62:63], v18, off offset:3328
	global_store_dwordx2 v[26:27], v[10:11], off offset:2560
	ds_read_b128 v[10:13], v74 offset:14336
	ds_read_b128 v[14:17], v73 offset:14336
	ds_read_b128 v[18:21], v73 offset:63488
	v_pk_mul_f32 v[22:23], v[8:9], v[68:69] op_sel_hi:[1,0]
	v_pk_mul_f32 v[24:25], v[6:7], v[68:69] op_sel_hi:[1,0]
	ds_read_b128 v[6:9], v74 offset:15360
	s_waitcnt lgkmcnt(3)
	v_pk_mul_f32 v[24:25], v[24:25], v[10:11]
	v_pk_mul_f32 v[22:23], v[22:23], v[12:13]
	ds_read_b128 v[10:13], v73 offset:64512
	s_waitcnt lgkmcnt(2)
	v_pk_add_f32 v[30:31], v[18:19], 1.0 op_sel_hi:[1,0]
	v_pk_add_f32 v[28:29], v[20:21], 1.0 op_sel_hi:[1,0]
	ds_read_b128 v[18:21], v73 offset:15360
	v_pk_fma_f32 v[14:15], v[24:25], v[30:31], v[14:15]
	v_mov_b32_e32 v30, 0
	v_med3_f32 v24, v14, s39, v72
	v_med3_f32 v25, v15, s39, v72
	v_cvt_pk_fp8_f32 v30, v24, v25
	v_pk_mul_f32 v[4:5], v[4:5], v[68:69] op_sel_hi:[1,0]
	v_pk_mul_f32 v[2:3], v[2:3], v[68:69] op_sel_hi:[1,0]
	v_pk_fma_f32 v[16:17], v[22:23], v[28:29], v[16:17]
	s_waitcnt lgkmcnt(2)
	v_pk_mul_f32 v[2:3], v[2:3], v[6:7]
	v_pk_mul_f32 v[4:5], v[4:5], v[8:9]
	s_waitcnt lgkmcnt(1)
	v_pk_add_f32 v[8:9], v[10:11], 1.0 op_sel_hi:[1,0]
	v_med3_f32 v22, v16, s39, v72
	v_med3_f32 v23, v17, s39, v72
	s_waitcnt lgkmcnt(0)
	v_pk_fma_f32 v[2:3], v[2:3], v[8:9], v[18:19]
	v_cvt_pk_fp8_f32 v30, v22, v23 op_sel:[0,0,1]
	v_bfe_u32 v22, v14, 16, 1
	v_med3_f32 v8, v2, s39, v72
	v_med3_f32 v9, v3, s39, v72
	v_mov_b32_e32 v10, 0
	v_add3_u32 v14, v14, v22, s40
	v_bfe_u32 v22, v15, 16, 1
	v_cvt_pk_fp8_f32 v10, v8, v9
	v_lshrrev_b32_e32 v14, 16, v14
	v_add3_u32 v15, v15, v22, s40
	v_pk_add_f32 v[6:7], v[12:13], 1.0 op_sel_hi:[1,0]
	v_and_or_b32 v14, v15, s41, v14
	v_bfe_u32 v15, v16, 16, 1
	v_pk_fma_f32 v[4:5], v[4:5], v[6:7], v[20:21]
	v_add3_u32 v15, v16, v15, s40
	v_bfe_u32 v16, v17, 16, 1
	v_med3_f32 v6, v4, s39, v72
	v_med3_f32 v7, v5, s39, v72
	v_lshrrev_b32_e32 v15, 16, v15
	v_cvt_pk_fp8_f32 v10, v6, v7 op_sel:[0,0,1]
	v_add3_u32 v6, v17, v16, s40
	v_and_or_b32 v15, v6, s41, v15
	v_bfe_u32 v6, v2, 16, 1
	v_add3_u32 v2, v2, v6, s40
	v_bfe_u32 v6, v3, 16, 1
	v_lshrrev_b32_e32 v2, 16, v2
	v_add3_u32 v3, v3, v6, s40
	v_and_or_b32 v2, v3, s41, v2
	v_bfe_u32 v3, v4, 16, 1
	v_add3_u32 v3, v4, v3, s40
	v_bfe_u32 v4, v5, 16, 1
	v_lshrrev_b32_e32 v3, 16, v3
	v_add3_u32 v4, v5, v4, s40
	v_and_or_b32 v3, v4, s41, v3
	global_store_dword v[62:63], v30, off offset:3584
	global_store_dwordx2 v[26:27], v[14:15], off offset:3072
	global_store_dword v[62:63], v10, off offset:3840
	global_store_dwordx2 v[26:27], v[2:3], off offset:3584
	s_addc_u32 s13, s13, s15
	s_add_u32 s16, s16, s18
	s_addc_u32 s17, s17, s19
	s_cmpk_gt_i32 s12, 0x41ff
	s_cbranch_scc1 .LBB0_223

.LBB0_225:
	v_ashrrev_i32_e32 v165, 31, v164
	v_lshlrev_b64 v[2:3], 7, v[164:165]
	v_lshl_add_u64 v[130:131], v[162:163], 0, v[2:3]
	v_add_u32_e32 v2, 1, v164
	v_add_u32_e32 v18, 2, v164
	v_ashrrev_i32_e32 v3, 31, v2
	v_ashrrev_i32_e32 v19, 31, v18
	v_lshlrev_b64 v[2:3], 7, v[2:3]
	v_lshlrev_b64 v[18:19], 7, v[18:19]
	v_add_u32_e32 v34, 3, v164
	global_load_dwordx4 v[98:101], v[130:131], off nt
	global_load_dwordx4 v[110:113], v[130:131], off offset:32 nt
	v_lshl_add_u64 v[132:133], v[162:163], 0, v[2:3]
	v_lshl_add_u64 v[134:135], v[162:163], 0, v[18:19]
	v_ashrrev_i32_e32 v35, 31, v34
	global_load_dwordx4 v[102:105], v[132:133], off nt
	global_load_dwordx4 v[114:117], v[132:133], off offset:32 nt
	global_load_dwordx4 v[106:109], v[134:135], off nt
	global_load_dwordx4 v[122:125], v[134:135], off offset:32 nt
	v_lshlrev_b64 v[34:35], 7, v[34:35]
	v_lshl_add_u64 v[166:167], v[162:163], 0, v[34:35]
	global_load_dwordx4 v[118:121], v[166:167], off nt
	global_load_dwordx4 v[126:129], v[166:167], off offset:32 nt
	global_load_dwordx4 v[154:157], v[130:131], off offset:64 nt
	global_load_dwordx4 v[158:161], v[130:131], off offset:96 nt
	global_load_dwordx4 v[146:149], v[132:133], off offset:64 nt
	global_load_dwordx4 v[150:153], v[132:133], off offset:96 nt
	global_load_dwordx4 v[138:141], v[134:135], off offset:64 nt
	global_load_dwordx4 v[142:145], v[134:135], off offset:96 nt
	v_mov_b32_e32 v172, v1
	global_load_dwordx4 v[134:137], v[166:167], off offset:64 nt
	global_load_dwordx4 v[130:133], v[166:167], off offset:96 nt
	v_cvt_f32_i32_e32 v170, v164
	v_and_b32_e32 v166, 0x7ff, v172
	v_cvt_f32_u32_e32 v166, v166
	s_waitcnt vmcnt(15)
	v_mfma_f32_32x32x16_bf16 v[2:17], v[66:69], v[98:101], 0
	v_fmamk_f32 v166, v166, 0xbbc49550, v169
	v_mul_f32_e64 v166, |v166|, s8
	v_exp_f32_e64 v167, -v166
	v_mul_f32_e64 v166, v166, -v170
	v_exp_f32_e32 v166, v166
	s_nop 0
	v_mul_f32_e32 v171, v167, v166
	s_waitcnt vmcnt(13)
	v_mfma_f32_32x32x16_bf16 v[18:33], v[66:69], v[102:105], 0
	v_mul_f32_e32 v173, v167, v171
	v_mul_f32_e32 v167, v167, v173
	s_waitcnt vmcnt(11)
	v_mfma_f32_32x32x16_bf16 v[34:49], v[66:69], v[106:109], 0
	s_waitcnt vmcnt(9)
	v_mfma_f32_32x32x16_bf16 v[50:65], v[66:69], v[118:121], 0
	v_mfma_f32_32x32x16_bf16 v[2:17], v[70:73], v[110:113], v[2:17]
	v_mfma_f32_32x32x16_bf16 v[18:33], v[70:73], v[114:117], v[18:33]
	v_mfma_f32_32x32x16_bf16 v[34:49], v[70:73], v[122:125], v[34:49]
	s_waitcnt vmcnt(8)
	v_mfma_f32_32x32x16_bf16 v[50:65], v[70:73], v[126:129], v[50:65]
	s_waitcnt vmcnt(7)
	v_mfma_f32_32x32x16_bf16 v[2:17], v[74:77], v[154:157], v[2:17]
	s_waitcnt vmcnt(5)
	v_mfma_f32_32x32x16_bf16 v[18:33], v[74:77], v[146:149], v[18:33]
	s_waitcnt vmcnt(3)
	v_mfma_f32_32x32x16_bf16 v[34:49], v[74:77], v[138:141], v[34:49]
	s_waitcnt vmcnt(1)
	v_mfma_f32_32x32x16_bf16 v[50:65], v[74:77], v[134:137], v[50:65]
	v_mfma_f32_32x32x16_bf16 v[2:17], v[78:81], v[158:161], v[2:17]
	v_mfma_f32_32x32x16_bf16 v[18:33], v[78:81], v[150:153], v[18:33]
	s_nop 10
	v_mul_f32_e32 v2, v2, v166
	v_mfma_f32_32x32x16_bf16 v[34:49], v[78:81], v[142:145], v[34:49]
	v_mul_f32_e32 v18, v18, v171
	v_cvt_pk_bf16_f32 v174, v2, v18
	s_waitcnt vmcnt(0)
	v_mfma_f32_32x32x16_bf16 v[50:65], v[78:81], v[130:133], v[50:65]
	s_nop 8
	v_mul_f32_e32 v2, v34, v173
	v_ashrrev_i32_e32 v173, 31, v172
	v_lshlrev_b64 v[172:173], 14, v[172:173]
	v_mul_f32_e32 v18, v50, v167
	v_lshl_add_u64 v[166:167], v[164:165], 1, s[6:7]
	v_cvt_pk_bf16_f32 v175, v2, v18
	v_lshl_add_u64 v[172:173], v[166:167], 0, v[172:173]
	v_mov_b32_e32 v2, v1
	global_store_dwordx2 v[172:173], v[174:175], off
	v_mov_b32_e32 v18, v1
	v_add_u32_e32 v172, 1, v2
	v_and_b32_e32 v2, 0x7ff, v172
	v_cvt_f32_u32_e32 v2, v2
	v_ashrrev_i32_e32 v173, 31, v172
	v_lshlrev_b64 v[172:173], 14, v[172:173]
	v_lshl_add_u64 v[172:173], v[166:167], 0, v[172:173]
	v_fmamk_f32 v2, v2, 0xbbc49550, v169
	v_mul_f32_e64 v2, |v2|, s8
	v_exp_f32_e64 v34, -v2
	v_mul_f32_e64 v2, v2, -v170
	v_exp_f32_e32 v2, v2
	s_nop 0
	v_mul_f32_e32 v50, v34, v2
	v_mul_f32_e32 v2, v3, v2
	v_mul_f32_e32 v3, v34, v50
	v_mul_f32_e32 v19, v19, v50
	v_mul_f32_e32 v34, v34, v3
	v_cvt_pk_bf16_f32 v2, v2, v19
	v_mul_f32_e32 v3, v35, v3
	v_mul_f32_e32 v19, v51, v34
	v_cvt_pk_bf16_f32 v3, v3, v19
	global_store_dwordx2 v[172:173], v[2:3], off
	v_mov_b32_e32 v34, v1
	v_add_u32_e32 v2, 2, v18
	v_and_b32_e32 v3, 0x7ff, v2
	v_cvt_f32_u32_e32 v3, v3
	v_fmamk_f32 v3, v3, 0xbbc49550, v169
	v_mul_f32_e64 v3, |v3|, s8
	v_exp_f32_e64 v18, -v3
	v_mul_f32_e64 v3, v3, -v170
	v_exp_f32_e32 v19, v3
	v_ashrrev_i32_e32 v3, 31, v2
	v_lshlrev_b64 v[2:3], 14, v[2:3]
	v_lshl_add_u64 v[2:3], v[166:167], 0, v[2:3]
	v_mul_f32_e32 v35, v18, v19
	v_mul_f32_e32 v4, v4, v19
	v_mul_f32_e32 v19, v18, v35
	v_mul_f32_e32 v20, v20, v35
	v_mul_f32_e32 v35, v18, v19
	v_cvt_pk_bf16_f32 v18, v4, v20
	v_mul_f32_e32 v4, v36, v19
	v_mul_f32_e32 v19, v52, v35
	v_cvt_pk_bf16_f32 v19, v4, v19
	global_store_dwordx2 v[2:3], v[18:19], off
	s_nop 0
	v_add_u32_e32 v2, 3, v34
	v_and_b32_e32 v3, 0x7ff, v2
	v_cvt_f32_u32_e32 v3, v3
	v_fmamk_f32 v3, v3, 0xbbc49550, v169
	v_mul_f32_e64 v3, |v3|, s8
	v_exp_f32_e64 v4, -v3
	v_mul_f32_e64 v3, v3, -v170
	v_exp_f32_e32 v18, v3
	v_ashrrev_i32_e32 v3, 31, v2
	v_lshlrev_b64 v[2:3], 14, v[2:3]
	v_lshl_add_u64 v[2:3], v[166:167], 0, v[2:3]
	v_mul_f32_e32 v19, v4, v18
	v_mul_f32_e32 v5, v5, v18
	v_mul_f32_e32 v18, v4, v19
	v_mul_f32_e32 v19, v21, v19
	v_mul_f32_e32 v20, v4, v18
	v_cvt_pk_bf16_f32 v4, v5, v19
	v_mul_f32_e32 v5, v37, v18
	v_mul_f32_e32 v18, v53, v20
	v_cvt_pk_bf16_f32 v5, v5, v18
	global_store_dwordx2 v[2:3], v[4:5], off
	v_mov_b32_e32 v2, v1
	s_nop 0
	v_add_u32_e32 v2, 8, v2
	v_and_b32_e32 v3, 0x7ff, v2
	v_cvt_f32_u32_e32 v3, v3
	v_fmamk_f32 v3, v3, 0xbbc49550, v169
	v_mul_f32_e64 v3, |v3|, s8
	v_exp_f32_e64 v4, -v3
	v_mul_f32_e64 v3, v3, -v170
	v_exp_f32_e32 v5, v3
	v_ashrrev_i32_e32 v3, 31, v2
	v_lshlrev_b64 v[2:3], 14, v[2:3]
	v_lshl_add_u64 v[2:3], v[166:167], 0, v[2:3]
	v_mul_f32_e32 v18, v4, v5
	v_mul_f32_e32 v5, v6, v5
	v_mul_f32_e32 v6, v4, v18
	v_mul_f32_e32 v18, v22, v18
	v_mul_f32_e32 v19, v4, v6
	v_cvt_pk_bf16_f32 v4, v5, v18
	v_mul_f32_e32 v5, v38, v6
	v_mul_f32_e32 v6, v54, v19
	v_cvt_pk_bf16_f32 v5, v5, v6
	global_store_dwordx2 v[2:3], v[4:5], off
	v_mov_b32_e32 v2, v1
	s_nop 0
	v_add_u32_e32 v2, 9, v2
	v_and_b32_e32 v3, 0x7ff, v2
	v_cvt_f32_u32_e32 v3, v3
	v_fmamk_f32 v3, v3, 0xbbc49550, v169
	v_mul_f32_e64 v3, |v3|, s8
	v_exp_f32_e64 v4, -v3
	v_mul_f32_e64 v3, v3, -v170
	v_exp_f32_e32 v3, v3
	s_nop 0
	v_mul_f32_e32 v5, v4, v3
	v_mul_f32_e32 v6, v4, v5
	v_mul_f32_e32 v3, v7, v3
	v_mul_f32_e32 v7, v4, v6
	v_mul_f32_e32 v4, v23, v5
	v_cvt_pk_bf16_f32 v4, v3, v4
	v_mul_f32_e32 v3, v39, v6
	v_mul_f32_e32 v5, v55, v7
	v_cvt_pk_bf16_f32 v5, v3, v5
	v_ashrrev_i32_e32 v3, 31, v2
	v_lshlrev_b64 v[2:3], 14, v[2:3]
	v_lshl_add_u64 v[2:3], v[166:167], 0, v[2:3]
	global_store_dwordx2 v[2:3], v[4:5], off
	v_mov_b32_e32 v2, v1
	s_nop 0
	v_add_u32_e32 v2, 10, v2
	v_and_b32_e32 v3, 0x7ff, v2
	v_cvt_f32_u32_e32 v3, v3
	v_fmamk_f32 v3, v3, 0xbbc49550, v169
	v_mul_f32_e64 v3, |v3|, s8
	v_exp_f32_e64 v4, -v3
	v_mul_f32_e64 v3, v3, -v170
	v_exp_f32_e32 v3, v3
	s_nop 0
	v_mul_f32_e32 v5, v4, v3
	v_mul_f32_e32 v6, v4, v5
	v_mul_f32_e32 v7, v4, v6
	v_mul_f32_e32 v3, v8, v3
	v_mul_f32_e32 v4, v24, v5
	v_cvt_pk_bf16_f32 v4, v3, v4
	v_mul_f32_e32 v3, v40, v6
	v_mul_f32_e32 v5, v56, v7
	v_cvt_pk_bf16_f32 v5, v3, v5
	v_ashrrev_i32_e32 v3, 31, v2
	v_lshlrev_b64 v[2:3], 14, v[2:3]
	v_lshl_add_u64 v[2:3], v[166:167], 0, v[2:3]
	global_store_dwordx2 v[2:3], v[4:5], off
	v_mov_b32_e32 v2, v1
	s_nop 0
	v_add_u32_e32 v2, 11, v2
	v_and_b32_e32 v3, 0x7ff, v2
	v_cvt_f32_u32_e32 v3, v3
	v_fmamk_f32 v3, v3, 0xbbc49550, v169
	v_mul_f32_e64 v3, |v3|, s8
	v_exp_f32_e64 v4, -v3
	v_mul_f32_e64 v3, v3, -v170
	v_exp_f32_e32 v3, v3
	s_nop 0
	v_mul_f32_e32 v5, v4, v3
	v_mul_f32_e32 v6, v4, v5
	v_mul_f32_e32 v7, v4, v6
	v_mul_f32_e32 v3, v9, v3
	v_mul_f32_e32 v4, v25, v5
	v_cvt_pk_bf16_f32 v4, v3, v4
	v_mul_f32_e32 v3, v41, v6
	v_mul_f32_e32 v5, v57, v7
	v_cvt_pk_bf16_f32 v5, v3, v5
	v_ashrrev_i32_e32 v3, 31, v2
	v_lshlrev_b64 v[2:3], 14, v[2:3]
	v_lshl_add_u64 v[2:3], v[166:167], 0, v[2:3]
	global_store_dwordx2 v[2:3], v[4:5], off
	v_mov_b32_e32 v2, v1
	s_nop 0
	v_add_u32_e32 v2, 16, v2
	v_and_b32_e32 v3, 0x7ff, v2
	v_cvt_f32_u32_e32 v3, v3
	v_fmamk_f32 v3, v3, 0xbbc49550, v169
	v_mul_f32_e64 v3, |v3|, s8
	v_exp_f32_e64 v4, -v3
	v_mul_f32_e64 v3, v3, -v170
	v_exp_f32_e32 v5, v3
	v_ashrrev_i32_e32 v3, 31, v2
	v_lshlrev_b64 v[2:3], 14, v[2:3]
	v_lshl_add_u64 v[2:3], v[166:167], 0, v[2:3]
	v_mul_f32_e32 v6, v4, v5
	v_mul_f32_e32 v5, v10, v5
	v_mul_f32_e32 v7, v4, v6
	v_mul_f32_e32 v6, v26, v6
	v_mul_f32_e32 v8, v4, v7
	v_cvt_pk_bf16_f32 v4, v5, v6
	v_mul_f32_e32 v5, v42, v7
	v_mul_f32_e32 v6, v58, v8
	v_cvt_pk_bf16_f32 v5, v5, v6
	global_store_dwordx2 v[2:3], v[4:5], off
	v_mov_b32_e32 v2, v1
	s_nop 0
	v_add_u32_e32 v2, 17, v2
	v_and_b32_e32 v3, 0x7ff, v2
	v_cvt_f32_u32_e32 v3, v3
	v_fmamk_f32 v3, v3, 0xbbc49550, v169
	v_mul_f32_e64 v3, |v3|, s8
	v_exp_f32_e64 v4, -v3
	v_mul_f32_e64 v3, v3, -v170
	v_exp_f32_e32 v3, v3
	s_nop 0
	v_mul_f32_e32 v5, v4, v3
	v_mul_f32_e32 v6, v4, v5
	v_mul_f32_e32 v3, v11, v3
	v_mul_f32_e32 v7, v4, v6
	v_mul_f32_e32 v4, v27, v5
	v_cvt_pk_bf16_f32 v4, v3, v4
	v_mul_f32_e32 v3, v43, v6
	v_mul_f32_e32 v5, v59, v7
	v_cvt_pk_bf16_f32 v5, v3, v5
	v_ashrrev_i32_e32 v3, 31, v2
	v_lshlrev_b64 v[2:3], 14, v[2:3]
	v_lshl_add_u64 v[2:3], v[166:167], 0, v[2:3]
	global_store_dwordx2 v[2:3], v[4:5], off
	v_mov_b32_e32 v2, v1
	s_nop 0
	v_add_u32_e32 v2, 18, v2
	v_and_b32_e32 v3, 0x7ff, v2
	v_cvt_f32_u32_e32 v3, v3
	v_fmamk_f32 v3, v3, 0xbbc49550, v169
	v_mul_f32_e64 v3, |v3|, s8
	v_exp_f32_e64 v4, -v3
	v_mul_f32_e64 v3, v3, -v170
	v_exp_f32_e32 v3, v3
	s_nop 0
	v_mul_f32_e32 v5, v4, v3
	v_mul_f32_e32 v6, v4, v5
	v_mul_f32_e32 v7, v4, v6
	v_mul_f32_e32 v3, v12, v3
	v_mul_f32_e32 v4, v28, v5
	v_cvt_pk_bf16_f32 v4, v3, v4
	v_mul_f32_e32 v3, v44, v6
	v_mul_f32_e32 v5, v60, v7
	v_cvt_pk_bf16_f32 v5, v3, v5
	v_ashrrev_i32_e32 v3, 31, v2
	v_lshlrev_b64 v[2:3], 14, v[2:3]
	v_lshl_add_u64 v[2:3], v[166:167], 0, v[2:3]
	global_store_dwordx2 v[2:3], v[4:5], off
	v_mov_b32_e32 v2, v1
	s_nop 0
	v_add_u32_e32 v2, 19, v2
	v_and_b32_e32 v3, 0x7ff, v2
	v_cvt_f32_u32_e32 v3, v3
	v_fmamk_f32 v3, v3, 0xbbc49550, v169
	v_mul_f32_e64 v3, |v3|, s8
	v_exp_f32_e64 v4, -v3
	v_mul_f32_e64 v3, v3, -v170
	v_exp_f32_e32 v3, v3
	s_nop 0
	v_mul_f32_e32 v5, v4, v3
	v_mul_f32_e32 v6, v4, v5
	v_mul_f32_e32 v7, v4, v6
	v_mul_f32_e32 v3, v13, v3
	v_mul_f32_e32 v4, v29, v5
	v_cvt_pk_bf16_f32 v4, v3, v4
	v_mul_f32_e32 v3, v45, v6
	v_mul_f32_e32 v5, v61, v7
	v_cvt_pk_bf16_f32 v5, v3, v5
	v_ashrrev_i32_e32 v3, 31, v2
	v_lshlrev_b64 v[2:3], 14, v[2:3]
	v_lshl_add_u64 v[2:3], v[166:167], 0, v[2:3]
	global_store_dwordx2 v[2:3], v[4:5], off
	v_mov_b32_e32 v2, v1
	s_nop 0
	v_add_u32_e32 v2, 24, v2
	v_and_b32_e32 v3, 0x7ff, v2
	v_cvt_f32_u32_e32 v3, v3
	v_fmamk_f32 v3, v3, 0xbbc49550, v169
	v_mul_f32_e64 v3, |v3|, s8
	v_exp_f32_e64 v4, -v3
	v_mul_f32_e64 v3, v3, -v170
	v_exp_f32_e32 v5, v3
	v_ashrrev_i32_e32 v3, 31, v2
	v_lshlrev_b64 v[2:3], 14, v[2:3]
	v_lshl_add_u64 v[2:3], v[166:167], 0, v[2:3]
	v_mul_f32_e32 v6, v4, v5
	v_mul_f32_e32 v5, v14, v5
	v_mul_f32_e32 v7, v4, v6
	v_mul_f32_e32 v6, v30, v6
	v_mul_f32_e32 v8, v4, v7
	v_cvt_pk_bf16_f32 v4, v5, v6
	v_mul_f32_e32 v5, v46, v7
	v_mul_f32_e32 v6, v62, v8
	v_cvt_pk_bf16_f32 v5, v5, v6
	global_store_dwordx2 v[2:3], v[4:5], off
	v_mov_b32_e32 v2, v1
	s_nop 0
	v_add_u32_e32 v2, 25, v2
	v_and_b32_e32 v3, 0x7ff, v2
	v_cvt_f32_u32_e32 v3, v3
	v_fmamk_f32 v3, v3, 0xbbc49550, v169
	v_mul_f32_e64 v3, |v3|, s8
	v_exp_f32_e64 v4, -v3
	v_mul_f32_e64 v3, v3, -v170
	v_exp_f32_e32 v3, v3
	s_nop 0
	v_mul_f32_e32 v5, v4, v3
	v_mul_f32_e32 v6, v4, v5
	v_mul_f32_e32 v3, v15, v3
	v_mul_f32_e32 v7, v4, v6
	v_mul_f32_e32 v4, v31, v5
	v_cvt_pk_bf16_f32 v4, v3, v4
	v_mul_f32_e32 v3, v47, v6
	v_mul_f32_e32 v5, v63, v7
	v_cvt_pk_bf16_f32 v5, v3, v5
	v_ashrrev_i32_e32 v3, 31, v2
	v_lshlrev_b64 v[2:3], 14, v[2:3]
	v_lshl_add_u64 v[2:3], v[166:167], 0, v[2:3]
	global_store_dwordx2 v[2:3], v[4:5], off
	v_mov_b32_e32 v2, v1
	s_nop 0
	v_add_u32_e32 v2, 26, v2
	v_and_b32_e32 v3, 0x7ff, v2
	v_cvt_f32_u32_e32 v3, v3
	v_fmamk_f32 v3, v3, 0xbbc49550, v169
	v_mul_f32_e64 v3, |v3|, s8
	v_exp_f32_e64 v4, -v3
	v_mul_f32_e64 v3, v3, -v170
	v_exp_f32_e32 v3, v3
	s_nop 0
	v_mul_f32_e32 v5, v4, v3
	v_mul_f32_e32 v6, v4, v5
	v_mul_f32_e32 v7, v4, v6
	v_mul_f32_e32 v3, v16, v3
	v_mul_f32_e32 v4, v32, v5
	v_cvt_pk_bf16_f32 v4, v3, v4
	v_mul_f32_e32 v3, v48, v6
	v_mul_f32_e32 v5, v64, v7
	v_cvt_pk_bf16_f32 v5, v3, v5
	v_ashrrev_i32_e32 v3, 31, v2
	v_lshlrev_b64 v[2:3], 14, v[2:3]
	v_lshl_add_u64 v[2:3], v[166:167], 0, v[2:3]
	global_store_dwordx2 v[2:3], v[4:5], off
	v_mov_b32_e32 v2, v1
	s_nop 0
	v_add_u32_e32 v2, 27, v2
	v_and_b32_e32 v3, 0x7ff, v2
	v_cvt_f32_u32_e32 v3, v3
	v_fmamk_f32 v3, v3, 0xbbc49550, v169
	v_mul_f32_e64 v3, |v3|, s8
	v_exp_f32_e64 v4, -v3
	v_mul_f32_e64 v3, v3, -v170
	v_exp_f32_e32 v3, v3
	s_nop 0
	v_mul_f32_e32 v5, v4, v3
	v_mul_f32_e32 v6, v4, v5
	v_mul_f32_e32 v7, v4, v6
	v_mul_f32_e32 v3, v17, v3
	v_mul_f32_e32 v4, v33, v5
	v_cvt_pk_bf16_f32 v4, v3, v4
	v_mul_f32_e32 v3, v49, v6
	v_mul_f32_e32 v5, v65, v7
	v_cvt_pk_bf16_f32 v5, v3, v5
	v_ashrrev_i32_e32 v3, 31, v2
	v_lshlrev_b64 v[2:3], 14, v[2:3]
	v_lshl_add_u64 v[2:3], v[166:167], 0, v[2:3]
	global_store_dwordx2 v[2:3], v[4:5], off
	v_mfma_f32_32x32x16_bf16 v[2:17], v[82:85], v[98:101], 0
	v_mov_b32_e32 v98, v168
	s_nop 0
	v_and_b32_e32 v99, 0x7ff, v98
	v_cvt_f32_u32_e32 v99, v99
	v_fmamk_f32 v99, v99, 0xbbc49550, v169
	v_mfma_f32_32x32x16_bf16 v[18:33], v[82:85], v[102:105], 0
	v_mul_f32_e64 v99, |v99|, s8
	v_exp_f32_e64 v100, -v99
	v_mul_f32_e64 v99, v99, -v170
	v_exp_f32_e32 v99, v99
	s_nop 0
	v_mul_f32_e32 v101, v100, v99
	v_mfma_f32_32x32x16_bf16 v[34:49], v[82:85], v[106:109], 0
	v_mul_f32_e32 v102, v100, v101
	v_mul_f32_e32 v103, v100, v102
	v_mfma_f32_32x32x16_bf16 v[50:65], v[82:85], v[118:121], 0
	v_mfma_f32_32x32x16_bf16 v[2:17], v[86:89], v[110:113], v[2:17]
	v_mfma_f32_32x32x16_bf16 v[18:33], v[86:89], v[114:117], v[18:33]
	v_mfma_f32_32x32x16_bf16 v[34:49], v[86:89], v[122:125], v[34:49]
	v_mfma_f32_32x32x16_bf16 v[50:65], v[86:89], v[126:129], v[50:65]
	v_mfma_f32_32x32x16_bf16 v[2:17], v[90:93], v[154:157], v[2:17]
	v_mfma_f32_32x32x16_bf16 v[18:33], v[90:93], v[146:149], v[18:33]
	v_mfma_f32_32x32x16_bf16 v[34:49], v[90:93], v[138:141], v[34:49]
	v_mfma_f32_32x32x16_bf16 v[50:65], v[90:93], v[134:137], v[50:65]
	v_mfma_f32_32x32x16_bf16 v[2:17], v[94:97], v[158:161], v[2:17]
	v_mfma_f32_32x32x16_bf16 v[18:33], v[94:97], v[150:153], v[18:33]
	s_nop 10
	v_mul_f32_e32 v2, v2, v99
	v_ashrrev_i32_e32 v99, 31, v98
	v_lshlrev_b64 v[98:99], 14, v[98:99]
	v_lshl_add_u64 v[98:99], v[166:167], 0, v[98:99]
	v_mfma_f32_32x32x16_bf16 v[34:49], v[94:97], v[142:145], v[34:49]
	v_mul_f32_e32 v18, v18, v101
	v_cvt_pk_bf16_f32 v100, v2, v18
	v_mfma_f32_32x32x16_bf16 v[50:65], v[94:97], v[130:133], v[50:65]
	s_nop 9
	v_mul_f32_e32 v2, v34, v102
	s_nop 0
	v_mul_f32_e32 v18, v50, v103
	v_cvt_pk_bf16_f32 v101, v2, v18
	v_mov_b32_e32 v2, v168
	global_store_dwordx2 v[98:99], v[100:101], off
	s_nop 0
	v_add_u32_e32 v2, 1, v2
	v_and_b32_e32 v18, 0x7ff, v2
	v_cvt_f32_u32_e32 v18, v18
	v_fmamk_f32 v18, v18, 0xbbc49550, v169
	v_mul_f32_e64 v18, |v18|, s8
	v_exp_f32_e64 v34, -v18
	v_mul_f32_e64 v18, v18, -v170
	v_exp_f32_e32 v18, v18
	s_nop 0
	v_mul_f32_e32 v50, v34, v18
	v_mul_f32_e32 v98, v34, v50
	v_mul_f32_e32 v34, v34, v98
	v_mul_f32_e32 v3, v3, v18
	v_mul_f32_e32 v18, v19, v50
	v_cvt_pk_bf16_f32 v18, v3, v18
	v_mul_f32_e32 v3, v35, v98
	v_mul_f32_e32 v19, v51, v34
	v_cvt_pk_bf16_f32 v19, v3, v19
	v_ashrrev_i32_e32 v3, 31, v2
	v_lshlrev_b64 v[2:3], 14, v[2:3]
	v_lshl_add_u64 v[2:3], v[166:167], 0, v[2:3]
	global_store_dwordx2 v[2:3], v[18:19], off
	v_mov_b32_e32 v2, v168
	s_nop 0
	v_add_u32_e32 v2, 2, v2
	v_and_b32_e32 v3, 0x7ff, v2
	v_cvt_f32_u32_e32 v3, v3
	v_fmamk_f32 v3, v3, 0xbbc49550, v169
	v_mul_f32_e64 v3, |v3|, s8
	v_exp_f32_e64 v18, -v3
	v_mul_f32_e64 v3, v3, -v170
	v_exp_f32_e32 v3, v3
	s_nop 0
	v_mul_f32_e32 v19, v18, v3
	v_mul_f32_e32 v34, v18, v19
	v_mul_f32_e32 v3, v4, v3
	v_mul_f32_e32 v35, v18, v34
	v_mul_f32_e32 v4, v20, v19
	v_cvt_pk_bf16_f32 v18, v3, v4
	v_mul_f32_e32 v3, v36, v34
	v_mul_f32_e32 v4, v52, v35
	v_cvt_pk_bf16_f32 v19, v3, v4
	v_ashrrev_i32_e32 v3, 31, v2
	v_lshlrev_b64 v[2:3], 14, v[2:3]
	v_lshl_add_u64 v[2:3], v[166:167], 0, v[2:3]
	global_store_dwordx2 v[2:3], v[18:19], off
	v_mov_b32_e32 v2, v168
	s_nop 0
	v_add_u32_e32 v2, 3, v2
	v_and_b32_e32 v3, 0x7ff, v2
	v_cvt_f32_u32_e32 v3, v3
	v_fmamk_f32 v3, v3, 0xbbc49550, v169
	v_mul_f32_e64 v3, |v3|, s8
	v_exp_f32_e64 v4, -v3
	v_mul_f32_e64 v3, v3, -v170
	v_exp_f32_e32 v3, v3
	s_nop 0
	v_mul_f32_e32 v18, v4, v3
	v_mul_f32_e32 v19, v4, v18
	v_mul_f32_e32 v20, v4, v19
	v_mul_f32_e32 v3, v5, v3
	v_mul_f32_e32 v4, v21, v18
	v_cvt_pk_bf16_f32 v4, v3, v4
	v_mul_f32_e32 v3, v37, v19
	v_mul_f32_e32 v5, v53, v20
	v_cvt_pk_bf16_f32 v5, v3, v5
	v_ashrrev_i32_e32 v3, 31, v2
	v_lshlrev_b64 v[2:3], 14, v[2:3]
	v_lshl_add_u64 v[2:3], v[166:167], 0, v[2:3]
	global_store_dwordx2 v[2:3], v[4:5], off
	v_mov_b32_e32 v2, v168
	s_nop 0
	v_add_u32_e32 v2, 8, v2
	v_and_b32_e32 v3, 0x7ff, v2
	v_cvt_f32_u32_e32 v3, v3
	v_fmamk_f32 v3, v3, 0xbbc49550, v169
	v_mul_f32_e64 v3, |v3|, s8
	v_exp_f32_e64 v4, -v3
	v_mul_f32_e64 v3, v3, -v170
	v_exp_f32_e32 v5, v3
	v_ashrrev_i32_e32 v3, 31, v2
	v_lshlrev_b64 v[2:3], 14, v[2:3]
	v_lshl_add_u64 v[2:3], v[166:167], 0, v[2:3]
	v_mul_f32_e32 v18, v4, v5
	v_mul_f32_e32 v5, v6, v5
	v_mul_f32_e32 v6, v4, v18
	v_mul_f32_e32 v18, v22, v18
	v_mul_f32_e32 v19, v4, v6
	v_cvt_pk_bf16_f32 v4, v5, v18
	v_mul_f32_e32 v5, v38, v6
	v_mul_f32_e32 v6, v54, v19
	v_cvt_pk_bf16_f32 v5, v5, v6
	global_store_dwordx2 v[2:3], v[4:5], off
	v_mov_b32_e32 v2, v168
	s_nop 0
	v_add_u32_e32 v2, 9, v2
	v_and_b32_e32 v3, 0x7ff, v2
	v_cvt_f32_u32_e32 v3, v3
	v_fmamk_f32 v3, v3, 0xbbc49550, v169
	v_mul_f32_e64 v3, |v3|, s8
	v_exp_f32_e64 v4, -v3
	v_mul_f32_e64 v3, v3, -v170
	v_exp_f32_e32 v3, v3
	s_nop 0
	v_mul_f32_e32 v5, v4, v3
	v_mul_f32_e32 v6, v4, v5
	v_mul_f32_e32 v3, v7, v3
	v_mul_f32_e32 v7, v4, v6
	v_mul_f32_e32 v4, v23, v5
	v_cvt_pk_bf16_f32 v4, v3, v4
	v_mul_f32_e32 v3, v39, v6
	v_mul_f32_e32 v5, v55, v7
	v_cvt_pk_bf16_f32 v5, v3, v5
	v_ashrrev_i32_e32 v3, 31, v2
	v_lshlrev_b64 v[2:3], 14, v[2:3]
	v_lshl_add_u64 v[2:3], v[166:167], 0, v[2:3]
	global_store_dwordx2 v[2:3], v[4:5], off
	v_mov_b32_e32 v2, v168
	s_nop 0
	v_add_u32_e32 v2, 10, v2
	v_and_b32_e32 v3, 0x7ff, v2
	v_cvt_f32_u32_e32 v3, v3
	v_fmamk_f32 v3, v3, 0xbbc49550, v169
	v_mul_f32_e64 v3, |v3|, s8
	v_exp_f32_e64 v4, -v3
	v_mul_f32_e64 v3, v3, -v170
	v_exp_f32_e32 v3, v3
	s_nop 0
	v_mul_f32_e32 v5, v4, v3
	v_mul_f32_e32 v6, v4, v5
	v_mul_f32_e32 v7, v4, v6
	v_mul_f32_e32 v3, v8, v3
	v_mul_f32_e32 v4, v24, v5
	v_cvt_pk_bf16_f32 v4, v3, v4
	v_mul_f32_e32 v3, v40, v6
	v_mul_f32_e32 v5, v56, v7
	v_cvt_pk_bf16_f32 v5, v3, v5
	v_ashrrev_i32_e32 v3, 31, v2
	v_lshlrev_b64 v[2:3], 14, v[2:3]
	v_lshl_add_u64 v[2:3], v[166:167], 0, v[2:3]
	global_store_dwordx2 v[2:3], v[4:5], off
	v_mov_b32_e32 v2, v168
	s_nop 0
	v_add_u32_e32 v2, 11, v2
	v_and_b32_e32 v3, 0x7ff, v2
	v_cvt_f32_u32_e32 v3, v3
	v_fmamk_f32 v3, v3, 0xbbc49550, v169
	v_mul_f32_e64 v3, |v3|, s8
	v_exp_f32_e64 v4, -v3
	v_mul_f32_e64 v3, v3, -v170
	v_exp_f32_e32 v3, v3
	s_nop 0
	v_mul_f32_e32 v5, v4, v3
	v_mul_f32_e32 v6, v4, v5
	v_mul_f32_e32 v7, v4, v6
	v_mul_f32_e32 v3, v9, v3
	v_mul_f32_e32 v4, v25, v5
	v_cvt_pk_bf16_f32 v4, v3, v4
	v_mul_f32_e32 v3, v41, v6
	v_mul_f32_e32 v5, v57, v7
	v_cvt_pk_bf16_f32 v5, v3, v5
	v_ashrrev_i32_e32 v3, 31, v2
	v_lshlrev_b64 v[2:3], 14, v[2:3]
	v_lshl_add_u64 v[2:3], v[166:167], 0, v[2:3]
	global_store_dwordx2 v[2:3], v[4:5], off
	v_mov_b32_e32 v2, v168
	s_nop 0
	v_add_u32_e32 v2, 16, v2
	v_and_b32_e32 v3, 0x7ff, v2
	v_cvt_f32_u32_e32 v3, v3
	v_fmamk_f32 v3, v3, 0xbbc49550, v169
	v_mul_f32_e64 v3, |v3|, s8
	v_exp_f32_e64 v4, -v3
	v_mul_f32_e64 v3, v3, -v170
	v_exp_f32_e32 v5, v3
	v_ashrrev_i32_e32 v3, 31, v2
	v_lshlrev_b64 v[2:3], 14, v[2:3]
	v_lshl_add_u64 v[2:3], v[166:167], 0, v[2:3]
	v_mul_f32_e32 v6, v4, v5
	v_mul_f32_e32 v5, v10, v5
	v_mul_f32_e32 v7, v4, v6
	v_mul_f32_e32 v6, v26, v6
	v_mul_f32_e32 v8, v4, v7
	v_cvt_pk_bf16_f32 v4, v5, v6
	v_mul_f32_e32 v5, v42, v7
	v_mul_f32_e32 v6, v58, v8
	v_cvt_pk_bf16_f32 v5, v5, v6
	global_store_dwordx2 v[2:3], v[4:5], off
	v_mov_b32_e32 v2, v168
	s_nop 0
	v_add_u32_e32 v2, 17, v2
	v_and_b32_e32 v3, 0x7ff, v2
	v_cvt_f32_u32_e32 v3, v3
	v_fmamk_f32 v3, v3, 0xbbc49550, v169
	v_mul_f32_e64 v3, |v3|, s8
	v_exp_f32_e64 v4, -v3
	v_mul_f32_e64 v3, v3, -v170
	v_exp_f32_e32 v3, v3
	s_nop 0
	v_mul_f32_e32 v5, v4, v3
	v_mul_f32_e32 v6, v4, v5
	v_mul_f32_e32 v3, v11, v3
	v_mul_f32_e32 v7, v4, v6
	v_mul_f32_e32 v4, v27, v5
	v_cvt_pk_bf16_f32 v4, v3, v4
	v_mul_f32_e32 v3, v43, v6
	v_mul_f32_e32 v5, v59, v7
	v_cvt_pk_bf16_f32 v5, v3, v5
	v_ashrrev_i32_e32 v3, 31, v2
	v_lshlrev_b64 v[2:3], 14, v[2:3]
	v_lshl_add_u64 v[2:3], v[166:167], 0, v[2:3]
	global_store_dwordx2 v[2:3], v[4:5], off
	v_mov_b32_e32 v2, v168
	s_nop 0
	v_add_u32_e32 v2, 18, v2
	v_and_b32_e32 v3, 0x7ff, v2
	v_cvt_f32_u32_e32 v3, v3
	v_fmamk_f32 v3, v3, 0xbbc49550, v169
	v_mul_f32_e64 v3, |v3|, s8
	v_exp_f32_e64 v4, -v3
	v_mul_f32_e64 v3, v3, -v170
	v_exp_f32_e32 v3, v3
	s_nop 0
	v_mul_f32_e32 v5, v4, v3
	v_mul_f32_e32 v6, v4, v5
	v_mul_f32_e32 v7, v4, v6
	v_mul_f32_e32 v3, v12, v3
	v_mul_f32_e32 v4, v28, v5
	v_cvt_pk_bf16_f32 v4, v3, v4
	v_mul_f32_e32 v3, v44, v6
	v_mul_f32_e32 v5, v60, v7
	v_cvt_pk_bf16_f32 v5, v3, v5
	v_ashrrev_i32_e32 v3, 31, v2
	v_lshlrev_b64 v[2:3], 14, v[2:3]
	v_lshl_add_u64 v[2:3], v[166:167], 0, v[2:3]
	global_store_dwordx2 v[2:3], v[4:5], off
	v_mov_b32_e32 v2, v168
	s_nop 0
	v_add_u32_e32 v2, 19, v2
	v_and_b32_e32 v3, 0x7ff, v2
	v_cvt_f32_u32_e32 v3, v3
	v_fmamk_f32 v3, v3, 0xbbc49550, v169
	v_mul_f32_e64 v3, |v3|, s8
	v_exp_f32_e64 v4, -v3
	v_mul_f32_e64 v3, v3, -v170
	v_exp_f32_e32 v3, v3
	s_nop 0
	v_mul_f32_e32 v5, v4, v3
	v_mul_f32_e32 v6, v4, v5
	v_mul_f32_e32 v7, v4, v6
	v_mul_f32_e32 v3, v13, v3
	v_mul_f32_e32 v4, v29, v5
	v_cvt_pk_bf16_f32 v4, v3, v4
	v_mul_f32_e32 v3, v45, v6
	v_mul_f32_e32 v5, v61, v7
	v_cvt_pk_bf16_f32 v5, v3, v5
	v_ashrrev_i32_e32 v3, 31, v2
	v_lshlrev_b64 v[2:3], 14, v[2:3]
	v_lshl_add_u64 v[2:3], v[166:167], 0, v[2:3]
	global_store_dwordx2 v[2:3], v[4:5], off
	v_mov_b32_e32 v2, v168
	s_nop 0
	v_add_u32_e32 v2, 24, v2
	v_and_b32_e32 v3, 0x7ff, v2
	v_cvt_f32_u32_e32 v3, v3
	v_fmamk_f32 v3, v3, 0xbbc49550, v169
	v_mul_f32_e64 v3, |v3|, s8
	v_exp_f32_e64 v4, -v3
	v_mul_f32_e64 v3, v3, -v170
	v_exp_f32_e32 v5, v3
	v_ashrrev_i32_e32 v3, 31, v2
	v_lshlrev_b64 v[2:3], 14, v[2:3]
	v_lshl_add_u64 v[2:3], v[166:167], 0, v[2:3]
	v_mul_f32_e32 v6, v4, v5
	v_mul_f32_e32 v5, v14, v5
	v_mul_f32_e32 v7, v4, v6
	v_mul_f32_e32 v6, v30, v6
	v_mul_f32_e32 v8, v4, v7
	v_cvt_pk_bf16_f32 v4, v5, v6
	v_mul_f32_e32 v5, v46, v7
	v_mul_f32_e32 v6, v62, v8
	v_cvt_pk_bf16_f32 v5, v5, v6
	global_store_dwordx2 v[2:3], v[4:5], off
	v_mov_b32_e32 v2, v168
	s_nop 0
	v_add_u32_e32 v2, 25, v2
	v_and_b32_e32 v3, 0x7ff, v2
	v_cvt_f32_u32_e32 v3, v3
	v_fmamk_f32 v3, v3, 0xbbc49550, v169
	v_mul_f32_e64 v3, |v3|, s8
	v_exp_f32_e64 v4, -v3
	v_mul_f32_e64 v3, v3, -v170
	v_exp_f32_e32 v3, v3
	s_nop 0
	v_mul_f32_e32 v5, v4, v3
	v_mul_f32_e32 v6, v4, v5
	v_mul_f32_e32 v3, v15, v3
	v_mul_f32_e32 v7, v4, v6
	v_mul_f32_e32 v4, v31, v5
	v_cvt_pk_bf16_f32 v4, v3, v4
	v_mul_f32_e32 v3, v47, v6
	v_mul_f32_e32 v5, v63, v7
	v_cvt_pk_bf16_f32 v5, v3, v5
	v_ashrrev_i32_e32 v3, 31, v2
	v_lshlrev_b64 v[2:3], 14, v[2:3]
	v_lshl_add_u64 v[2:3], v[166:167], 0, v[2:3]
	global_store_dwordx2 v[2:3], v[4:5], off
	v_mov_b32_e32 v2, v168
	s_nop 0
	v_add_u32_e32 v2, 26, v2
	v_and_b32_e32 v3, 0x7ff, v2
	v_cvt_f32_u32_e32 v3, v3
	v_fmamk_f32 v3, v3, 0xbbc49550, v169
	v_mul_f32_e64 v3, |v3|, s8
	v_exp_f32_e64 v4, -v3
	v_mul_f32_e64 v3, v3, -v170
	v_exp_f32_e32 v3, v3
	s_nop 0
	v_mul_f32_e32 v5, v4, v3
	v_mul_f32_e32 v6, v4, v5
	v_mul_f32_e32 v7, v4, v6
	v_mul_f32_e32 v3, v16, v3
	v_mul_f32_e32 v4, v32, v5
	v_cvt_pk_bf16_f32 v4, v3, v4
	v_mul_f32_e32 v3, v48, v6
	v_mul_f32_e32 v5, v64, v7
	v_cvt_pk_bf16_f32 v5, v3, v5
	v_ashrrev_i32_e32 v3, 31, v2
	v_lshlrev_b64 v[2:3], 14, v[2:3]
	v_lshl_add_u64 v[2:3], v[166:167], 0, v[2:3]
	global_store_dwordx2 v[2:3], v[4:5], off
	v_mov_b32_e32 v2, v168
	s_nop 0
	v_add_u32_e32 v2, 27, v2
	v_and_b32_e32 v3, 0x7ff, v2
	v_cvt_f32_u32_e32 v3, v3
	v_fmamk_f32 v3, v3, 0xbbc49550, v169
	v_mul_f32_e64 v3, |v3|, s8
	v_exp_f32_e64 v4, -v3
	v_mul_f32_e64 v3, v3, -v170
	v_exp_f32_e32 v3, v3
	s_nop 0
	v_mul_f32_e32 v5, v4, v3
	v_mul_f32_e32 v6, v4, v5
	v_mul_f32_e32 v7, v4, v6
	v_mul_f32_e32 v3, v17, v3
	v_mul_f32_e32 v4, v33, v5
	v_cvt_pk_bf16_f32 v4, v3, v4
	v_mul_f32_e32 v3, v49, v6
	v_mul_f32_e32 v5, v65, v7
	v_cvt_pk_bf16_f32 v5, v3, v5
	v_ashrrev_i32_e32 v3, 31, v2
	v_lshlrev_b64 v[2:3], 14, v[2:3]
	v_lshl_add_u64 v[2:3], v[166:167], 0, v[2:3]
	global_store_dwordx2 v[2:3], v[4:5], off
	s_add_i32 s3, s3, s4
	s_cmp_gt_i32 s3, 7
	v_add_u32_e32 v164, s5, v164
	s_cbranch_scc0 .LBB0_225

.LBB0_875:
	v_mov_b32_e32 v3, v1
	s_ashr_i32 s6, s8, 31
	v_lshlrev_b32_e32 v2, 5, v3
	v_lshlrev_b32_e32 v5, 4, v3
	v_lshlrev_b32_e32 v6, 7, v3
	v_ashrrev_i32_e32 v4, 2, v3
	v_add_u32_e32 v7, 64, v3
	v_ashrrev_i32_e32 v3, 31, v2
	v_and_b32_e32 v34, 48, v5
	v_add_u32_e32 v37, s4, v6
	v_ashrrev_i32_e32 v5, 31, v4
	v_lshl_add_u64 v[38:39], v[2:3], 2, s[16:17]
	v_add_u32_e32 v32, 0x800, v2
	ds_read_b128 v[8:11], v37
	ds_read_b128 v[12:15], v37 offset:16
	ds_read_b128 v[16:19], v37 offset:32
	ds_read_b128 v[20:23], v37 offset:48
	ds_read_b128 v[24:27], v37 offset:64
	ds_read_b128 v[28:31], v37 offset:80
	ds_read_b128 v[44:47], v37 offset:96
	ds_read_b128 v[48:51], v37 offset:112
	v_lshlrev_b64 v[112:113], 7, v[4:5]
	global_load_dwordx4 v[2:5], v[38:39], off nt
	global_load_dwordx4 v[52:55], v[38:39], off offset:16 nt
	global_load_dwordx4 v[56:59], v[38:39], off offset:32 nt
	global_load_dwordx4 v[60:63], v[38:39], off offset:48 nt
	global_load_dwordx4 v[64:67], v[38:39], off offset:64 nt
	global_load_dwordx4 v[68:71], v[38:39], off offset:80 nt
	global_load_dwordx4 v[72:75], v[38:39], off offset:96 nt
	global_load_dwordx4 v[76:79], v[38:39], off offset:112 nt
	v_ashrrev_i32_e32 v33, 31, v32
	v_lshl_add_u64 v[32:33], v[32:33], 2, s[16:17]
	global_load_dwordx4 v[80:83], v[32:33], off nt
	global_load_dwordx4 v[84:87], v[32:33], off offset:16 nt
	global_load_dwordx4 v[88:91], v[32:33], off offset:48 nt
	global_load_dwordx4 v[92:95], v[32:33], off offset:32 nt
	global_load_dwordx4 v[96:99], v[32:33], off offset:112 nt
	global_load_dwordx4 v[100:103], v[32:33], off offset:96 nt
	global_load_dwordx4 v[104:107], v[32:33], off offset:80 nt
	global_load_dwordx4 v[108:111], v[32:33], off offset:64 nt
	s_lshr_b32 s6, s6, 19
	s_add_i32 s6, s8, s6
	s_lshl_b32 s6, s6, 1
	s_and_b32 s6, s6, 0xffffc000
	s_add_i32 s6, s6, 0
	v_or_b32_e32 v112, v112, v34
	v_add_u32_e32 v6, s6, v6
	v_lshl_add_u64 v[38:39], s[12:13], 0, v[112:113]
	ds_read_b128 v[112:115], v6
	ds_read_b128 v[116:119], v6 offset:16
	ds_read_b128 v[120:123], v6 offset:32
	ds_read_b128 v[124:127], v6 offset:48
	ds_read_b128 v[128:131], v6 offset:32768
	ds_read_b128 v[132:135], v6 offset:32784
	ds_read_b128 v[136:139], v6 offset:32800
	ds_read_b128 v[140:143], v6 offset:32816
	ds_read_b128 v[144:147], v6 offset:64
	ds_read_b128 v[148:151], v6 offset:80
	ds_read_b128 v[152:155], v6 offset:32832
	ds_read_b128 v[156:159], v6 offset:32848
	ds_read_b128 v[160:163], v6 offset:96
	ds_read_b128 v[164:167], v6 offset:112
	ds_read_b128 v[168:171], v6 offset:32864
	ds_read_b128 v[172:175], v6 offset:32880
	v_ashrrev_i32_e32 v36, 2, v7
	v_ashrrev_i32_e32 v37, 31, v36
	v_lshlrev_b64 v[36:37], 7, v[36:37]
	v_lshlrev_b32_e32 v43, 7, v7
	v_or_b32_e32 v36, v36, v34
	s_waitcnt lgkmcnt(11)
	v_pk_add_f32 v[6:7], v[130:131], 1.0 op_sel_hi:[1,0]
	v_pk_add_f32 v[32:33], v[128:129], 1.0 op_sel_hi:[1,0]
	s_waitcnt lgkmcnt(10)
	v_pk_add_f32 v[128:129], v[134:135], 1.0 op_sel_hi:[1,0]
	v_pk_add_f32 v[130:131], v[132:133], 1.0 op_sel_hi:[1,0]
	s_waitcnt lgkmcnt(9)
	v_pk_add_f32 v[132:133], v[138:139], 1.0 op_sel_hi:[1,0]
	v_pk_add_f32 v[134:135], v[136:137], 1.0 op_sel_hi:[1,0]
	s_waitcnt lgkmcnt(8)
	v_pk_add_f32 v[136:137], v[142:143], 1.0 op_sel_hi:[1,0]
	v_pk_add_f32 v[138:139], v[140:141], 1.0 op_sel_hi:[1,0]
	s_waitcnt lgkmcnt(5)
	v_pk_add_f32 v[140:141], v[154:155], 1.0 op_sel_hi:[1,0]
	v_pk_add_f32 v[142:143], v[152:153], 1.0 op_sel_hi:[1,0]
	s_waitcnt lgkmcnt(4)
	v_pk_add_f32 v[152:153], v[158:159], 1.0 op_sel_hi:[1,0]
	v_pk_add_f32 v[154:155], v[156:157], 1.0 op_sel_hi:[1,0]
	s_waitcnt lgkmcnt(1)
	v_pk_add_f32 v[156:157], v[170:171], 1.0 op_sel_hi:[1,0]
	v_pk_add_f32 v[158:159], v[168:169], 1.0 op_sel_hi:[1,0]
	s_waitcnt lgkmcnt(0)
	v_pk_add_f32 v[168:169], v[174:175], 1.0 op_sel_hi:[1,0]
	v_pk_add_f32 v[170:171], v[172:173], 1.0 op_sel_hi:[1,0]
	v_add_u32_e32 v200, s4, v43
	v_add_u32_e32 v43, s6, v43
	s_add_i32 s8, s8, s10
	v_lshl_add_u64 v[36:37], s[12:13], 0, v[36:37]
	s_add_u32 s12, s12, s14
	s_addc_u32 s13, s13, s15
	s_add_u32 s16, s16, s18
	s_addc_u32 s17, s17, s19
	s_cmpk_gt_i32 s8, 0x3fff
	s_waitcnt vmcnt(15)
	v_mul_f32_e32 v34, v3, v3
	v_mul_f32_e32 v172, v5, v5
	s_waitcnt vmcnt(14)
	v_mul_f32_e32 v173, v53, v53
	v_mul_f32_e32 v174, v55, v55
	s_waitcnt vmcnt(13)
	v_mul_f32_e32 v175, v57, v57
	v_mul_f32_e32 v176, v59, v59
	v_fmac_f32_e32 v34, v2, v2
	v_fmac_f32_e32 v172, v4, v4
	v_fmac_f32_e32 v173, v52, v52
	v_fmac_f32_e32 v174, v54, v54
	s_waitcnt vmcnt(12)
	v_mul_f32_e32 v177, v61, v61
	v_mul_f32_e32 v178, v63, v63
	v_fmac_f32_e32 v175, v56, v56
	v_fmac_f32_e32 v176, v58, v58
	v_add_f32_e32 v34, v34, v172
	v_add_f32_e32 v172, v173, v174
	s_waitcnt vmcnt(11)
	v_mul_f32_e32 v179, v65, v65
	v_mul_f32_e32 v180, v67, v67
	v_fmac_f32_e32 v177, v60, v60
	v_fmac_f32_e32 v178, v62, v62
	v_add_f32_e32 v173, v175, v176
	v_add_f32_e32 v34, v34, v172
	s_waitcnt vmcnt(10)
	v_mul_f32_e32 v181, v69, v69
	v_mul_f32_e32 v182, v71, v71
	v_fmac_f32_e32 v179, v64, v64
	v_fmac_f32_e32 v180, v66, v66
	v_add_f32_e32 v174, v177, v178
	v_add_f32_e32 v34, v34, v173
	s_waitcnt vmcnt(9)
	v_mul_f32_e32 v183, v73, v73
	v_mul_f32_e32 v184, v75, v75
	v_fmac_f32_e32 v181, v68, v68
	v_fmac_f32_e32 v182, v70, v70
	v_add_f32_e32 v175, v179, v180
	v_add_f32_e32 v34, v34, v174
	s_waitcnt vmcnt(8)
	v_mul_f32_e32 v185, v77, v77
	v_mul_f32_e32 v186, v79, v79
	v_fmac_f32_e32 v183, v72, v72
	v_fmac_f32_e32 v184, v74, v74
	v_add_f32_e32 v176, v181, v182
	v_add_f32_e32 v34, v34, v175
	v_fmac_f32_e32 v185, v76, v76
	v_fmac_f32_e32 v186, v78, v78
	s_waitcnt vmcnt(7)
	v_mul_f32_e32 v187, v81, v81
	v_mul_f32_e32 v188, v83, v83
	v_add_f32_e32 v177, v183, v184
	v_add_f32_e32 v34, v34, v176
	s_waitcnt vmcnt(6)
	v_mul_f32_e32 v189, v85, v85
	v_mul_f32_e32 v190, v87, v87
	v_add_f32_e32 v178, v185, v186
	v_fmac_f32_e32 v187, v80, v80
	v_fmac_f32_e32 v188, v82, v82
	v_add_f32_e32 v34, v34, v177
	s_waitcnt vmcnt(4)
	v_mul_f32_e32 v191, v93, v93
	v_mul_f32_e32 v192, v95, v95
	v_fmac_f32_e32 v189, v84, v84
	v_fmac_f32_e32 v190, v86, v86
	v_add_f32_e32 v172, v187, v188
	v_add_f32_e32 v34, v34, v178
	v_mul_f32_e32 v193, v89, v89
	v_mul_f32_e32 v194, v91, v91
	v_fmac_f32_e32 v191, v92, v92
	v_fmac_f32_e32 v192, v94, v94
	v_add_f32_e32 v179, v189, v190
	v_add_f32_e32 v34, v34, v172
	s_waitcnt vmcnt(0)
	v_mul_f32_e32 v195, v109, v109
	v_mul_f32_e32 v196, v111, v111
	v_fmac_f32_e32 v193, v88, v88
	v_fmac_f32_e32 v194, v90, v90
	v_add_f32_e32 v180, v191, v192
	v_add_f32_e32 v34, v34, v179
	v_mul_f32_e32 v197, v105, v105
	v_mul_f32_e32 v198, v107, v107
	v_fmac_f32_e32 v195, v108, v108
	v_fmac_f32_e32 v196, v110, v110
	v_add_f32_e32 v181, v193, v194
	v_add_f32_e32 v34, v34, v180
	v_mul_f32_e32 v199, v101, v101
	v_mul_f32_e32 v201, v103, v103
	v_fmac_f32_e32 v197, v104, v104
	v_fmac_f32_e32 v198, v106, v106
	v_add_f32_e32 v182, v195, v196
	v_add_f32_e32 v34, v34, v181
	v_mul_f32_e32 v202, v97, v97
	v_mul_f32_e32 v203, v99, v99
	v_fmac_f32_e32 v199, v100, v100
	v_fmac_f32_e32 v201, v102, v102
	v_add_f32_e32 v183, v197, v198
	v_add_f32_e32 v34, v34, v182
	v_fmac_f32_e32 v202, v96, v96
	v_fmac_f32_e32 v203, v98, v98
	v_add_f32_e32 v184, v199, v201
	v_add_f32_e32 v34, v34, v183
	v_add_f32_e32 v185, v202, v203
	v_add_f32_e32 v34, v34, v184
	v_add_f32_e32 v34, v34, v185
	ds_swizzle_b32 v172, v34 offset:swizzle(SWAP,1)
	s_waitcnt lgkmcnt(0)
	v_add_f32_e32 v34, v34, v172
	ds_swizzle_b32 v172, v34 offset:swizzle(SWAP,2)
	s_waitcnt lgkmcnt(0)
	v_add_f32_e32 v34, v34, v172
	ds_swizzle_b32 v172, v34 offset:swizzle(SWAP,4)
	s_waitcnt lgkmcnt(0)
	v_add_f32_e32 v34, v34, v172
	ds_swizzle_b32 v172, v34 offset:swizzle(SWAP,8)
	s_waitcnt lgkmcnt(0)
	v_add_f32_e32 v34, v34, v172
	ds_swizzle_b32 v172, v34 offset:swizzle(SWAP,16)
	s_waitcnt lgkmcnt(0)
	v_add_f32_e32 v34, v34, v172
	v_mov_b32_e32 v172, v34
	s_nop 1
	v_permlane32_swap_b32_e32 v34, v172
	v_add_f32_e32 v34, v34, v172
	v_fmamk_f32 v34, v34, 0x39800000, v40
	v_mul_f32_e32 v172, 0x4f800000, v34
	v_cmp_gt_f32_e32 vcc, s3, v34
	s_nop 1
	v_cndmask_b32_e32 v34, v34, v172, vcc
	v_sqrt_f32_e32 v172, v34
	s_nop 0
	v_add_u32_e32 v173, -1, v172
	v_add_u32_e32 v174, 1, v172
	v_fma_f32 v175, -v173, v172, v34
	v_fma_f32 v176, -v174, v172, v34
	v_cmp_ge_f32_e64 s[6:7], 0, v175
	s_nop 1
	v_cndmask_b32_e64 v172, v172, v173, s[6:7]
	v_cmp_lt_f32_e64 s[6:7], 0, v176
	s_nop 1
	v_cndmask_b32_e64 v172, v172, v174, s[6:7]
	v_mul_f32_e32 v173, 0x37800000, v172
	v_cndmask_b32_e32 v172, v172, v173, vcc
	v_cmp_class_f32_e32 vcc, v34, v41
	s_nop 1
	v_cndmask_b32_e32 v34, v172, v34, vcc
	v_div_scale_f32 v172, s[6:7], v34, v34, 1.0
	v_rcp_f32_e32 v174, v172
	v_div_scale_f32 v173, vcc, 1.0, v34, 1.0
	v_fma_f32 v175, -v172, v174, 1.0
	v_fmac_f32_e32 v174, v175, v174
	v_mul_f32_e32 v175, v173, v174
	v_fma_f32 v176, -v172, v175, v173
	v_fmac_f32_e32 v175, v176, v174
	v_fma_f32 v172, -v172, v175, v173
	v_div_fmas_f32 v172, v172, v174, v175
	v_div_fixup_f32 v34, v172, v34, 1.0
	v_pk_mul_f32 v[2:3], v[2:3], v[34:35] op_sel_hi:[1,0]
	v_pk_mul_f32 v[52:53], v[52:53], v[34:35] op_sel_hi:[1,0]
	v_pk_mul_f32 v[56:57], v[56:57], v[34:35] op_sel_hi:[1,0]
	v_pk_mul_f32 v[60:61], v[60:61], v[34:35] op_sel_hi:[1,0]
	v_pk_mul_f32 v[64:65], v[64:65], v[34:35] op_sel_hi:[1,0]
	v_pk_mul_f32 v[4:5], v[4:5], v[34:35] op_sel_hi:[1,0]
	v_pk_mul_f32 v[54:55], v[54:55], v[34:35] op_sel_hi:[1,0]
	v_pk_mul_f32 v[58:59], v[58:59], v[34:35] op_sel_hi:[1,0]
	v_pk_mul_f32 v[62:63], v[62:63], v[34:35] op_sel_hi:[1,0]
	v_pk_mul_f32 v[66:67], v[66:67], v[34:35] op_sel_hi:[1,0]
	v_pk_mul_f32 v[68:69], v[68:69], v[34:35] op_sel_hi:[1,0]
	v_pk_mul_f32 v[72:73], v[72:73], v[34:35] op_sel_hi:[1,0]
	v_pk_mul_f32 v[76:77], v[76:77], v[34:35] op_sel_hi:[1,0]
	v_pk_mul_f32 v[2:3], v[8:9], v[2:3]
	v_pk_mul_f32 v[8:9], v[12:13], v[52:53]
	v_pk_mul_f32 v[12:13], v[16:17], v[56:57]
	v_pk_mul_f32 v[16:17], v[60:61], v[20:21]
	v_pk_mul_f32 v[20:21], v[64:65], v[24:25]
	v_pk_mul_f32 v[70:71], v[70:71], v[34:35] op_sel_hi:[1,0]
	v_pk_mul_f32 v[74:75], v[74:75], v[34:35] op_sel_hi:[1,0]
	v_pk_mul_f32 v[78:79], v[78:79], v[34:35] op_sel_hi:[1,0]
	v_pk_mul_f32 v[4:5], v[10:11], v[4:5]
	v_pk_mul_f32 v[10:11], v[14:15], v[54:55]
	v_pk_mul_f32 v[14:15], v[18:19], v[58:59]
	v_pk_mul_f32 v[18:19], v[62:63], v[22:23]
	v_pk_mul_f32 v[22:23], v[66:67], v[26:27]
	v_pk_mul_f32 v[24:25], v[68:69], v[28:29]
	v_pk_mul_f32 v[28:29], v[72:73], v[44:45]
	v_pk_mul_f32 v[44:45], v[76:77], v[48:49]
	v_pk_fma_f32 v[2:3], v[32:33], v[2:3], v[112:113]
	v_pk_fma_f32 v[20:21], v[142:143], v[20:21], v[144:145]
	v_pk_mul_f32 v[110:111], v[110:111], v[34:35] op_sel_hi:[1,0]
	v_pk_mul_f32 v[108:109], v[108:109], v[34:35] op_sel_hi:[1,0]
	v_pk_mul_f32 v[172:173], v[106:107], v[34:35] op_sel_hi:[1,0]
	v_pk_mul_f32 v[174:175], v[104:105], v[34:35] op_sel_hi:[1,0]
	v_pk_mul_f32 v[176:177], v[102:103], v[34:35] op_sel_hi:[1,0]
	v_pk_mul_f32 v[178:179], v[100:101], v[34:35] op_sel_hi:[1,0]
	v_pk_mul_f32 v[180:181], v[98:99], v[34:35] op_sel_hi:[1,0]
	v_pk_mul_f32 v[182:183], v[96:97], v[34:35] op_sel_hi:[1,0]
	v_pk_mul_f32 v[184:185], v[82:83], v[34:35] op_sel_hi:[1,0]
	v_pk_mul_f32 v[186:187], v[80:81], v[34:35] op_sel_hi:[1,0]
	v_pk_mul_f32 v[188:189], v[86:87], v[34:35] op_sel_hi:[1,0]
	v_pk_mul_f32 v[190:191], v[84:85], v[34:35] op_sel_hi:[1,0]
	v_pk_mul_f32 v[192:193], v[94:95], v[34:35] op_sel_hi:[1,0]
	v_pk_mul_f32 v[194:195], v[92:93], v[34:35] op_sel_hi:[1,0]
	v_pk_mul_f32 v[196:197], v[90:91], v[34:35] op_sel_hi:[1,0]
	v_pk_mul_f32 v[198:199], v[88:89], v[34:35] op_sel_hi:[1,0]
	v_pk_mul_f32 v[26:27], v[70:71], v[30:31]
	v_pk_mul_f32 v[30:31], v[74:75], v[46:47]
	v_pk_mul_f32 v[46:47], v[78:79], v[50:51]
	v_pk_fma_f32 v[4:5], v[6:7], v[4:5], v[114:115]
	v_pk_fma_f32 v[6:7], v[128:129], v[10:11], v[118:119]
	v_pk_fma_f32 v[10:11], v[132:133], v[14:15], v[122:123]
	v_pk_fma_f32 v[14:15], v[136:137], v[18:19], v[126:127]
	v_pk_fma_f32 v[18:19], v[140:141], v[22:23], v[146:147]
	v_pk_fma_f32 v[32:33], v[170:171], v[44:45], v[164:165]
	v_max_f32_e64 v34, |v2|, |v20|
	v_max_f32_e64 v44, |v3|, |v21|
	v_pk_fma_f32 v[8:9], v[130:131], v[8:9], v[116:117]
	v_pk_fma_f32 v[22:23], v[152:153], v[26:27], v[150:151]
	v_pk_fma_f32 v[24:25], v[154:155], v[24:25], v[148:149]
	v_pk_fma_f32 v[26:27], v[156:157], v[30:31], v[162:163]
	v_pk_fma_f32 v[30:31], v[168:169], v[46:47], v[166:167]
	v_max_f32_e64 v45, |v4|, |v18|
	v_max_f32_e64 v46, |v5|, |v19|
	v_max3_f32 v34, v34, 0, v44
	v_max_f32_e64 v47, |v8|, |v24|
	v_max_f32_e64 v48, |v9|, |v25|
	v_max3_f32 v34, v34, v45, v46
	v_pk_fma_f32 v[12:13], v[134:135], v[12:13], v[120:121]
	v_pk_fma_f32 v[28:29], v[158:159], v[28:29], v[160:161]
	v_max_f32_e64 v49, |v6|, |v22|
	v_max_f32_e64 v50, |v7|, |v23|
	v_max3_f32 v34, v34, v47, v48
	v_max_f32_e64 v51, |v12|, |v28|
	v_max_f32_e64 v52, |v13|, |v29|
	v_max3_f32 v34, v34, v49, v50
	v_pk_fma_f32 v[16:17], v[138:139], v[16:17], v[124:125]
	v_max_f32_e64 v53, |v10|, |v26|
	v_max_f32_e64 v54, |v11|, |v27|
	v_max3_f32 v34, v34, v51, v52
	v_max_f32_e64 v55, |v16|, |v32|
	v_max_f32_e64 v56, |v17|, |v33|
	v_max3_f32 v34, v34, v53, v54
	v_max_f32_e64 v57, |v14|, |v30|
	v_max_f32_e64 v58, |v15|, |v31|
	v_max3_f32 v34, v34, v55, v56
	v_max3_f32 v34, v34, v57, v58
	v_bfe_u32 v34, v34, 23, 8
	v_max_u32_e32 v34, 3, v34
	v_lshlrev_b32_e32 v44, 23, v34
	v_sub_u32_e32 v44, 0x80000000, v44
	v_mul_f32_e32 v2, v2, v44
	v_mul_f32_e32 v20, v20, v44
	v_mul_f32_e32 v3, v3, v44
	v_mul_f32_e32 v21, v21, v44
	v_mul_f32_e32 v4, v4, v44
	v_mul_f32_e32 v45, v18, v44
	v_mul_f32_e32 v5, v5, v44
	v_mul_f32_e32 v46, v19, v44
	v_mul_f32_e32 v8, v8, v44
	v_mul_f32_e32 v24, v24, v44
	v_mul_f32_e32 v9, v9, v44
	v_mul_f32_e32 v25, v25, v44
	v_mul_f32_e32 v47, v6, v44
	v_mul_f32_e32 v48, v22, v44
	v_mul_f32_e32 v49, v7, v44
	v_mul_f32_e32 v50, v23, v44
	v_mul_f32_e32 v12, v12, v44
	v_mul_f32_e32 v28, v28, v44
	v_mul_f32_e32 v13, v13, v44
	v_mul_f32_e32 v29, v29, v44
	v_mul_f32_e32 v51, v10, v44
	v_mul_f32_e32 v52, v26, v44
	v_mul_f32_e32 v53, v11, v44
	v_mul_f32_e32 v54, v27, v44
	v_mul_f32_e32 v16, v16, v44
	v_mul_f32_e32 v32, v32, v44
	v_mul_f32_e32 v17, v17, v44
	v_mul_f32_e32 v33, v33, v44
	v_mul_f32_e32 v55, v14, v44
	v_mul_f32_e32 v56, v30, v44
	v_mul_f32_e32 v57, v15, v44
	v_mul_f32_e32 v44, v31, v44
	v_med3_f32 v2, v2, s5, v42
	v_med3_f32 v18, v20, s5, v42
	v_med3_f32 v3, v3, s5, v42
	v_med3_f32 v19, v21, s5, v42
	v_med3_f32 v4, v4, s5, v42
	v_med3_f32 v20, v45, s5, v42
	v_med3_f32 v5, v5, s5, v42
	v_med3_f32 v21, v46, s5, v42
	v_med3_f32 v6, v8, s5, v42
	v_med3_f32 v22, v24, s5, v42
	v_med3_f32 v7, v9, s5, v42
	v_med3_f32 v23, v25, s5, v42
	v_med3_f32 v8, v47, s5, v42
	v_med3_f32 v24, v48, s5, v42
	v_med3_f32 v9, v49, s5, v42
	v_med3_f32 v25, v50, s5, v42
	v_med3_f32 v10, v12, s5, v42
	v_med3_f32 v26, v28, s5, v42
	v_med3_f32 v11, v13, s5, v42
	v_med3_f32 v27, v29, s5, v42
	v_med3_f32 v12, v51, s5, v42
	v_med3_f32 v28, v52, s5, v42
	v_med3_f32 v13, v53, s5, v42
	v_med3_f32 v29, v54, s5, v42
	v_med3_f32 v14, v16, s5, v42
	v_med3_f32 v30, v32, s5, v42
	v_med3_f32 v15, v17, s5, v42
	v_med3_f32 v31, v33, s5, v42
	v_med3_f32 v16, v55, s5, v42
	v_med3_f32 v32, v56, s5, v42
	v_med3_f32 v17, v57, s5, v42
	v_med3_f32 v33, v44, s5, v42
	v_cvt_scalef32_2xpk16_fp6_f32 v[2:7], v[2:17], v[18:33], 1.0
	v_add_u32_e32 v34, -2, v34
	v_mov_b32_e32 v32, v6
	v_mov_b32_e32 v33, v7
	global_store_dwordx4 v[38:39], v[2:5], off offset:-64
	global_store_dwordx4 v[38:39], v[32:35], off
	ds_read_b128 v[2:5], v43
	ds_read_b128 v[6:9], v43 offset:16
	ds_read_b128 v[10:13], v43 offset:32
	ds_read_b128 v[14:17], v43 offset:48
	ds_read_b128 v[18:21], v200
	ds_read_b128 v[22:25], v200 offset:16
	ds_read_b128 v[26:29], v200 offset:32
	ds_read_b128 v[30:33], v200 offset:48
	ds_read_b128 v[44:47], v43 offset:32768
	ds_read_b128 v[48:51], v43 offset:32784
	ds_read_b128 v[52:55], v43 offset:32800
	ds_read_b128 v[56:59], v43 offset:32816
	ds_read_b128 v[60:63], v43 offset:64
	ds_read_b128 v[64:67], v43 offset:80
	ds_read_b128 v[68:71], v43 offset:32832
	ds_read_b128 v[72:75], v43 offset:32848
	ds_read_b128 v[76:79], v200 offset:64
	ds_read_b128 v[80:83], v200 offset:80
	ds_read_b128 v[84:87], v43 offset:96
	ds_read_b128 v[88:91], v43 offset:112
	ds_read_b128 v[92:95], v43 offset:32864
	ds_read_b128 v[96:99], v43 offset:32880
	ds_read_b128 v[100:103], v200 offset:96
	ds_read_b128 v[104:107], v200 offset:112
	s_waitcnt lgkmcnt(9)
	v_pk_add_f32 v[38:39], v[70:71], 1.0 op_sel_hi:[1,0]
	v_pk_add_f32 v[68:69], v[68:69], 1.0 op_sel_hi:[1,0]
	s_waitcnt lgkmcnt(7)
	v_pk_mul_f32 v[70:71], v[108:109], v[76:77]
	v_pk_add_f32 v[44:45], v[44:45], 1.0 op_sel_hi:[1,0]
	v_pk_mul_f32 v[18:19], v[186:187], v[18:19]
	v_pk_mul_f32 v[76:77], v[110:111], v[78:79]
	v_pk_add_f32 v[46:47], v[46:47], 1.0 op_sel_hi:[1,0]
	v_pk_mul_f32 v[20:21], v[184:185], v[20:21]
	v_pk_fma_f32 v[60:61], v[68:69], v[70:71], v[60:61]
	v_pk_fma_f32 v[2:3], v[44:45], v[18:19], v[2:3]
	v_pk_add_f32 v[72:73], v[72:73], 1.0 op_sel_hi:[1,0]
	s_waitcnt lgkmcnt(6)
	v_pk_mul_f32 v[78:79], v[174:175], v[80:81]
	v_pk_add_f32 v[48:49], v[48:49], 1.0 op_sel_hi:[1,0]
	v_pk_mul_f32 v[22:23], v[190:191], v[22:23]
	v_pk_fma_f32 v[38:39], v[38:39], v[76:77], v[62:63]
	v_pk_fma_f32 v[4:5], v[46:47], v[20:21], v[4:5]
	v_max_f32_e64 v18, |v2|, |v60|
	v_max_f32_e64 v19, |v3|, |v61|
	v_pk_add_f32 v[74:75], v[74:75], 1.0 op_sel_hi:[1,0]
	v_pk_mul_f32 v[80:81], v[172:173], v[82:83]
	v_pk_add_f32 v[50:51], v[50:51], 1.0 op_sel_hi:[1,0]
	v_pk_mul_f32 v[24:25], v[188:189], v[24:25]
	v_pk_fma_f32 v[64:65], v[72:73], v[78:79], v[64:65]
	v_pk_fma_f32 v[6:7], v[48:49], v[22:23], v[6:7]
	v_max_f32_e64 v20, |v4|, |v38|
	v_max_f32_e64 v21, |v5|, |v39|
	v_max3_f32 v18, v18, 0, v19
	s_waitcnt lgkmcnt(3)
	v_pk_add_f32 v[82:83], v[94:95], 1.0 op_sel_hi:[1,0]
	v_pk_add_f32 v[92:93], v[92:93], 1.0 op_sel_hi:[1,0]
	s_waitcnt lgkmcnt(1)
	v_pk_mul_f32 v[94:95], v[178:179], v[100:101]
	v_pk_add_f32 v[52:53], v[52:53], 1.0 op_sel_hi:[1,0]
	v_pk_mul_f32 v[26:27], v[194:195], v[26:27]
	v_pk_fma_f32 v[62:63], v[74:75], v[80:81], v[66:67]
	v_pk_fma_f32 v[8:9], v[50:51], v[24:25], v[8:9]
	v_max_f32_e64 v22, |v6|, |v64|
	v_max_f32_e64 v23, |v7|, |v65|
	v_max3_f32 v18, v18, v20, v21
	v_pk_mul_f32 v[100:101], v[176:177], v[102:103]
	v_pk_add_f32 v[54:55], v[54:55], 1.0 op_sel_hi:[1,0]
	v_pk_mul_f32 v[28:29], v[192:193], v[28:29]
	v_pk_fma_f32 v[68:69], v[92:93], v[94:95], v[84:85]
	v_pk_fma_f32 v[10:11], v[52:53], v[26:27], v[10:11]
	v_max_f32_e64 v24, |v8|, |v62|
	v_max_f32_e64 v25, |v9|, |v63|
	v_max3_f32 v18, v18, v22, v23
	v_pk_add_f32 v[96:97], v[96:97], 1.0 op_sel_hi:[1,0]
	s_waitcnt lgkmcnt(0)
	v_pk_mul_f32 v[102:103], v[182:183], v[104:105]
	v_pk_add_f32 v[56:57], v[56:57], 1.0 op_sel_hi:[1,0]
	v_pk_mul_f32 v[30:31], v[198:199], v[30:31]
	v_pk_fma_f32 v[66:67], v[82:83], v[100:101], v[86:87]
	v_pk_fma_f32 v[12:13], v[54:55], v[28:29], v[12:13]
	v_max_f32_e64 v26, |v10|, |v68|
	v_max_f32_e64 v27, |v11|, |v69|
	v_max3_f32 v18, v18, v24, v25
	v_pk_add_f32 v[98:99], v[98:99], 1.0 op_sel_hi:[1,0]
	v_pk_mul_f32 v[104:105], v[180:181], v[106:107]
	v_pk_add_f32 v[58:59], v[58:59], 1.0 op_sel_hi:[1,0]
	v_pk_mul_f32 v[32:33], v[196:197], v[32:33]
	v_pk_fma_f32 v[72:73], v[96:97], v[102:103], v[88:89]
	v_pk_fma_f32 v[14:15], v[56:57], v[30:31], v[14:15]
	v_max_f32_e64 v28, |v12|, |v66|
	v_max_f32_e64 v29, |v13|, |v67|
	v_max3_f32 v18, v18, v26, v27
	v_pk_fma_f32 v[70:71], v[98:99], v[104:105], v[90:91]
	v_pk_fma_f32 v[16:17], v[58:59], v[32:33], v[16:17]
	v_max_f32_e64 v30, |v14|, |v72|
	v_max_f32_e64 v31, |v15|, |v73|
	v_max3_f32 v18, v18, v28, v29
	v_max_f32_e64 v32, |v16|, |v70|
	v_max_f32_e64 v33, |v17|, |v71|
	v_max3_f32 v18, v18, v30, v31
	v_max3_f32 v18, v18, v32, v33
	v_bfe_u32 v18, v18, 23, 8
	v_max_u32_e32 v18, 3, v18
	v_lshlrev_b32_e32 v19, 23, v18
	v_add_u32_e32 v34, -2, v18
	v_sub_u32_e32 v18, 0x80000000, v19
	v_mul_f32_e32 v2, v2, v18
	v_mul_f32_e32 v19, v60, v18
	v_mul_f32_e32 v3, v3, v18
	v_mul_f32_e32 v20, v61, v18
	v_mul_f32_e32 v4, v4, v18
	v_mul_f32_e32 v21, v38, v18
	v_mul_f32_e32 v5, v5, v18
	v_mul_f32_e32 v22, v39, v18
	v_mul_f32_e32 v6, v6, v18
	v_mul_f32_e32 v23, v64, v18
	v_mul_f32_e32 v7, v7, v18
	v_mul_f32_e32 v24, v65, v18
	v_mul_f32_e32 v8, v8, v18
	v_mul_f32_e32 v25, v62, v18
	v_mul_f32_e32 v9, v9, v18
	v_mul_f32_e32 v26, v63, v18
	v_mul_f32_e32 v10, v10, v18
	v_mul_f32_e32 v27, v68, v18
	v_mul_f32_e32 v11, v11, v18
	v_mul_f32_e32 v28, v69, v18
	v_mul_f32_e32 v12, v12, v18
	v_mul_f32_e32 v29, v66, v18
	v_mul_f32_e32 v13, v13, v18
	v_mul_f32_e32 v30, v67, v18
	v_mul_f32_e32 v14, v14, v18
	v_mul_f32_e32 v31, v72, v18
	v_mul_f32_e32 v15, v15, v18
	v_mul_f32_e32 v32, v73, v18
	v_mul_f32_e32 v16, v16, v18
	v_mul_f32_e32 v33, v70, v18
	v_mul_f32_e32 v17, v17, v18
	v_mul_f32_e32 v38, v71, v18
	v_med3_f32 v2, v2, s5, v42
	v_med3_f32 v18, v19, s5, v42
	v_med3_f32 v3, v3, s5, v42
	v_med3_f32 v19, v20, s5, v42
	v_med3_f32 v4, v4, s5, v42
	v_med3_f32 v20, v21, s5, v42
	v_med3_f32 v5, v5, s5, v42
	v_med3_f32 v21, v22, s5, v42
	v_med3_f32 v6, v6, s5, v42
	v_med3_f32 v22, v23, s5, v42
	v_med3_f32 v7, v7, s5, v42
	v_med3_f32 v23, v24, s5, v42
	v_med3_f32 v8, v8, s5, v42
	v_med3_f32 v24, v25, s5, v42
	v_med3_f32 v9, v9, s5, v42
	v_med3_f32 v25, v26, s5, v42
	v_med3_f32 v10, v10, s5, v42
	v_med3_f32 v26, v27, s5, v42
	v_med3_f32 v11, v11, s5, v42
	v_med3_f32 v27, v28, s5, v42
	v_med3_f32 v12, v12, s5, v42
	v_med3_f32 v28, v29, s5, v42
	v_med3_f32 v13, v13, s5, v42
	v_med3_f32 v29, v30, s5, v42
	v_med3_f32 v14, v14, s5, v42
	v_med3_f32 v30, v31, s5, v42
	v_med3_f32 v15, v15, s5, v42
	v_med3_f32 v31, v32, s5, v42
	v_med3_f32 v16, v16, s5, v42
	v_med3_f32 v32, v33, s5, v42
	v_med3_f32 v17, v17, s5, v42
	v_med3_f32 v33, v38, s5, v42
	v_cvt_scalef32_2xpk16_fp6_f32 v[2:7], v[2:17], v[18:33], 1.0
	v_mov_b32_e32 v32, v6
	v_mov_b32_e32 v33, v7
	global_store_dwordx4 v[36:37], v[2:5], off offset:-64
	global_store_dwordx4 v[36:37], v[32:35], off
	s_cbranch_scc0 .LBB0_875
